# speedup vs baseline: 1.0431x; 1.0222x over previous
; __device__ __forceinline__ float u8f(unsigned w, int i) { return (float)((w >> (8 * i)) & 0xffu) * (1.f / 255.f); }
; __device__ void phase4(const Params& p) {
;     ...
;       const size_t lanef = (size_t)(fo_e + wr * 64 + fq * 4);
;       if (seg == 0) {
;         #pragma unroll
;         for (int bj = 0; bj < 2; ++bj)
;           #pragma unroll
;           for (int n = 0; n < 2; ++n) {
;             const size_t base = (size_t)EPI_T(bj, n) * D + lanef;
;             const unsigned* pa = reinterpret_cast<const unsigned*>(reinterpret_cast<const unsigned char*>(sga) + base);
;             const unsigned* pb = reinterpret_cast<const unsigned*>(reinterpret_cast<const unsigned char*>(sgb) + base);
;             #pragma unroll
;             for (int ai = 0; ai < 2; ++ai)
;               #pragma unroll
;               for (int m = 0; m < 4; ++m) {
;                 const unsigned ga = pa[(ai * 128 + m * 16) / 4];
;                 const unsigned gb = pb[(ai * 128 + m * 16) / 4];
;                 #pragma unroll
;                 for (int j = 0; j < 4; ++j)
;                   acc[ai][bj][m][n][j] *= u8f(ga, j) * __builtin_amdgcn_rcpf(fmaxf(u8f(gb, j), 1e-30f));
;               }
.LBB0_608:
	s_or_b64 exec, exec, s[50:51]
	v_and_b32_e32 v132, 15, v194
	v_lshrrev_b32_e32 v133, 1, v194
	v_and_b32_e32 v133, 0x60, v133
	v_add3_u32 v132, s18, v132, v133
	v_bfe_u32 v134, v194, 4, 2
	v_lshrrev_b32_e32 v135, 2, v194
	v_and_b32_e32 v135, 0xffffffc0, v135
	v_lshl_add_u32 v136, v134, 4, v135
	v_add_u32_e32 v136, s20, v136
	v_lshl_add_u32 v136, v132, 11, v136
	v_add_u32_e32 v137, 0x8000, v136
	v_add_u32_e32 v138, 0x40000, v136
	v_add_u32_e32 v139, 0x48000, v136
	s_cmp_lg_u32 s79, 0
	s_cbranch_scc1 .Lp4e_seg1
	global_load_dwordx4 v[152:155], v136, s[10:11]
	global_load_dwordx4 v[156:159], v136, s[12:13]
	global_load_dwordx4 v[160:163], v136, s[10:11] offset:128
	global_load_dwordx4 v[164:167], v136, s[12:13] offset:128
	global_load_dwordx4 v[168:171], v137, s[10:11]
	global_load_dwordx4 v[172:175], v137, s[12:13]
	global_load_dwordx4 v[176:179], v137, s[10:11] offset:128
	global_load_dwordx4 v[180:183], v137, s[12:13] offset:128
	global_load_dwordx4 v[184:187], v138, s[10:11]
	global_load_dwordx4 v[188:191], v138, s[12:13]
	global_load_dwordx4 v[196:199], v138, s[10:11] offset:128
	global_load_dwordx4 v[200:203], v138, s[12:13] offset:128
	global_load_dwordx4 v[204:207], v139, s[10:11]
	global_load_dwordx4 v[208:211], v139, s[12:13]
	global_load_dwordx4 v[212:215], v139, s[10:11] offset:128
	global_load_dwordx4 v[216:219], v139, s[12:13] offset:128
	s_waitcnt vmcnt(14)
	v_permlane16_swap_b32 v152, v153
	v_permlane16_swap_b32 v154, v155
	v_permlane16_swap_b32 v156, v157
	v_permlane16_swap_b32 v158, v159
	v_permlane32_swap_b32 v152, v154
	v_permlane32_swap_b32 v153, v155
	v_permlane32_swap_b32 v156, v158
	v_permlane32_swap_b32 v157, v159
	v_cvt_f32_ubyte0_e32 v144, v156
	v_cvt_f32_ubyte1_e32 v145, v156
	v_cvt_f32_ubyte2_e32 v146, v156
	v_cvt_f32_ubyte3_e32 v147, v156
	v_cvt_f32_ubyte0_e32 v140, v152
	v_cvt_f32_ubyte1_e32 v141, v152
	v_cvt_f32_ubyte2_e32 v142, v152
	v_cvt_f32_ubyte3_e32 v143, v152
	v_pk_mul_f32 v[144:145], v[144:145], s[16:17] op_sel_hi:[1,0]
	v_pk_mul_f32 v[146:147], v[146:147], s[16:17] op_sel_hi:[1,0]
	v_pk_mul_f32 v[140:141], v[140:141], s[16:17] op_sel_hi:[1,0]
	v_pk_mul_f32 v[142:143], v[142:143], s[16:17] op_sel_hi:[1,0]
	v_max_f32_e32 v144, 0xda24260, v144
	v_max_f32_e32 v145, 0xda24260, v145
	v_max_f32_e32 v146, 0xda24260, v146
	v_max_f32_e32 v147, 0xda24260, v147
	v_rcp_f32_e32 v144, v144
	v_rcp_f32_e32 v145, v145
	v_rcp_f32_e32 v146, v146
	v_rcp_f32_e32 v147, v147
	v_pk_mul_f32 v[140:141], v[140:141], v[144:145]
	v_pk_mul_f32 v[142:143], v[142:143], v[146:147]
	v_pk_mul_f32 v[128:129], v[128:129], v[140:141]
	v_pk_mul_f32 v[130:131], v[130:131], v[142:143]
	v_cvt_f32_ubyte0_e32 v144, v157
	v_cvt_f32_ubyte1_e32 v145, v157
	v_cvt_f32_ubyte2_e32 v146, v157
	v_cvt_f32_ubyte3_e32 v147, v157
	v_cvt_f32_ubyte0_e32 v140, v153
	v_cvt_f32_ubyte1_e32 v141, v153
	v_cvt_f32_ubyte2_e32 v142, v153
	v_cvt_f32_ubyte3_e32 v143, v153
	v_pk_mul_f32 v[144:145], v[144:145], s[16:17] op_sel_hi:[1,0]
	v_pk_mul_f32 v[146:147], v[146:147], s[16:17] op_sel_hi:[1,0]
	v_pk_mul_f32 v[140:141], v[140:141], s[16:17] op_sel_hi:[1,0]
	v_pk_mul_f32 v[142:143], v[142:143], s[16:17] op_sel_hi:[1,0]
	v_max_f32_e32 v144, 0xda24260, v144
	v_max_f32_e32 v145, 0xda24260, v145
	v_max_f32_e32 v146, 0xda24260, v146
	v_max_f32_e32 v147, 0xda24260, v147
	v_rcp_f32_e32 v144, v144
	v_rcp_f32_e32 v145, v145
	v_rcp_f32_e32 v146, v146
	v_rcp_f32_e32 v147, v147
	v_pk_mul_f32 v[140:141], v[140:141], v[144:145]
	v_pk_mul_f32 v[142:143], v[142:143], v[146:147]
	v_pk_mul_f32 v[120:121], v[120:121], v[140:141]
	v_pk_mul_f32 v[122:123], v[122:123], v[142:143]
	v_cvt_f32_ubyte0_e32 v144, v158
	v_cvt_f32_ubyte1_e32 v145, v158
	v_cvt_f32_ubyte2_e32 v146, v158
	v_cvt_f32_ubyte3_e32 v147, v158
	v_cvt_f32_ubyte0_e32 v140, v154
	v_cvt_f32_ubyte1_e32 v141, v154
	v_cvt_f32_ubyte2_e32 v142, v154
	v_cvt_f32_ubyte3_e32 v143, v154
	v_pk_mul_f32 v[144:145], v[144:145], s[16:17] op_sel_hi:[1,0]
	v_pk_mul_f32 v[146:147], v[146:147], s[16:17] op_sel_hi:[1,0]
	v_pk_mul_f32 v[140:141], v[140:141], s[16:17] op_sel_hi:[1,0]
	v_pk_mul_f32 v[142:143], v[142:143], s[16:17] op_sel_hi:[1,0]
	v_max_f32_e32 v144, 0xda24260, v144
	v_max_f32_e32 v145, 0xda24260, v145
	v_max_f32_e32 v146, 0xda24260, v146
	v_max_f32_e32 v147, 0xda24260, v147
	v_rcp_f32_e32 v144, v144
	v_rcp_f32_e32 v145, v145
	v_rcp_f32_e32 v146, v146
	v_rcp_f32_e32 v147, v147
	v_pk_mul_f32 v[140:141], v[140:141], v[144:145]
	v_pk_mul_f32 v[142:143], v[142:143], v[146:147]
	v_pk_mul_f32 v[112:113], v[112:113], v[140:141]
	v_pk_mul_f32 v[114:115], v[114:115], v[142:143]
	v_cvt_f32_ubyte0_e32 v144, v159
	v_cvt_f32_ubyte1_e32 v145, v159
	v_cvt_f32_ubyte2_e32 v146, v159
	v_cvt_f32_ubyte3_e32 v147, v159
	v_cvt_f32_ubyte0_e32 v140, v155
	v_cvt_f32_ubyte1_e32 v141, v155
	v_cvt_f32_ubyte2_e32 v142, v155
	v_cvt_f32_ubyte3_e32 v143, v155
	v_pk_mul_f32 v[144:145], v[144:145], s[16:17] op_sel_hi:[1,0]
	v_pk_mul_f32 v[146:147], v[146:147], s[16:17] op_sel_hi:[1,0]
	v_pk_mul_f32 v[140:141], v[140:141], s[16:17] op_sel_hi:[1,0]
	v_pk_mul_f32 v[142:143], v[142:143], s[16:17] op_sel_hi:[1,0]
	v_max_f32_e32 v144, 0xda24260, v144
	v_max_f32_e32 v145, 0xda24260, v145
	v_max_f32_e32 v146, 0xda24260, v146
	v_max_f32_e32 v147, 0xda24260, v147
	v_rcp_f32_e32 v144, v144
	v_rcp_f32_e32 v145, v145
	v_rcp_f32_e32 v146, v146
	v_rcp_f32_e32 v147, v147
	v_pk_mul_f32 v[140:141], v[140:141], v[144:145]
	v_pk_mul_f32 v[142:143], v[142:143], v[146:147]
	v_pk_mul_f32 v[104:105], v[104:105], v[140:141]
	v_pk_mul_f32 v[106:107], v[106:107], v[142:143]
	s_waitcnt vmcnt(12)
; __device__ __forceinline__ float u8f(unsigned w, int i) { return (float)((w >> (8 * i)) & 0xffu) * (1.f / 255.f); }
; __device__ void phase4(const Params& p) {
;     ...
;             #pragma unroll
;             for (int ai = 0; ai < 2; ++ai)
;               #pragma unroll
;               for (int m = 0; m < 4; ++m) {
;                 const unsigned ga = pa[(ai * 128 + m * 16) / 4];
;                 const unsigned gb = pb[(ai * 128 + m * 16) / 4];
;                 #pragma unroll
;                 for (int j = 0; j < 4; ++j)
;                   acc[ai][bj][m][n][j] *= u8f(ga, j) * __builtin_amdgcn_rcpf(fmaxf(u8f(gb, j), 1e-30f));
	v_permlane16_swap_b32 v160, v161
	v_permlane16_swap_b32 v162, v163
	v_permlane16_swap_b32 v164, v165
	v_permlane16_swap_b32 v166, v167
	v_permlane32_swap_b32 v160, v162
	v_permlane32_swap_b32 v161, v163
	v_permlane32_swap_b32 v164, v166
	v_permlane32_swap_b32 v165, v167
	v_cvt_f32_ubyte0_e32 v144, v164
	v_cvt_f32_ubyte1_e32 v145, v164
	v_cvt_f32_ubyte2_e32 v146, v164
	v_cvt_f32_ubyte3_e32 v147, v164
	v_cvt_f32_ubyte0_e32 v140, v160
	v_cvt_f32_ubyte1_e32 v141, v160
	v_cvt_f32_ubyte2_e32 v142, v160
	v_cvt_f32_ubyte3_e32 v143, v160
	v_pk_mul_f32 v[144:145], v[144:145], s[16:17] op_sel_hi:[1,0]
	v_pk_mul_f32 v[146:147], v[146:147], s[16:17] op_sel_hi:[1,0]
	v_pk_mul_f32 v[140:141], v[140:141], s[16:17] op_sel_hi:[1,0]
	v_pk_mul_f32 v[142:143], v[142:143], s[16:17] op_sel_hi:[1,0]
	v_max_f32_e32 v144, 0xda24260, v144
	v_max_f32_e32 v145, 0xda24260, v145
	v_max_f32_e32 v146, 0xda24260, v146
	v_max_f32_e32 v147, 0xda24260, v147
	v_rcp_f32_e32 v144, v144
	v_rcp_f32_e32 v145, v145
	v_rcp_f32_e32 v146, v146
	v_rcp_f32_e32 v147, v147
	v_pk_mul_f32 v[140:141], v[140:141], v[144:145]
	v_pk_mul_f32 v[142:143], v[142:143], v[146:147]
	v_pk_mul_f32 v[64:65], v[64:65], v[140:141]
	v_pk_mul_f32 v[66:67], v[66:67], v[142:143]
	v_cvt_f32_ubyte0_e32 v144, v165
	v_cvt_f32_ubyte1_e32 v145, v165
	v_cvt_f32_ubyte2_e32 v146, v165
	v_cvt_f32_ubyte3_e32 v147, v165
	v_cvt_f32_ubyte0_e32 v140, v161
	v_cvt_f32_ubyte1_e32 v141, v161
	v_cvt_f32_ubyte2_e32 v142, v161
	v_cvt_f32_ubyte3_e32 v143, v161
	v_pk_mul_f32 v[144:145], v[144:145], s[16:17] op_sel_hi:[1,0]
	v_pk_mul_f32 v[146:147], v[146:147], s[16:17] op_sel_hi:[1,0]
	v_pk_mul_f32 v[140:141], v[140:141], s[16:17] op_sel_hi:[1,0]
	v_pk_mul_f32 v[142:143], v[142:143], s[16:17] op_sel_hi:[1,0]
	v_max_f32_e32 v144, 0xda24260, v144
	v_max_f32_e32 v145, 0xda24260, v145
	v_max_f32_e32 v146, 0xda24260, v146
	v_max_f32_e32 v147, 0xda24260, v147
	v_rcp_f32_e32 v144, v144
	v_rcp_f32_e32 v145, v145
	v_rcp_f32_e32 v146, v146
	v_rcp_f32_e32 v147, v147
	v_pk_mul_f32 v[140:141], v[140:141], v[144:145]
	v_pk_mul_f32 v[142:143], v[142:143], v[146:147]
	v_pk_mul_f32 v[56:57], v[56:57], v[140:141]
	v_pk_mul_f32 v[58:59], v[58:59], v[142:143]
	v_cvt_f32_ubyte0_e32 v144, v166
	v_cvt_f32_ubyte1_e32 v145, v166
	v_cvt_f32_ubyte2_e32 v146, v166
	v_cvt_f32_ubyte3_e32 v147, v166
	v_cvt_f32_ubyte0_e32 v140, v162
	v_cvt_f32_ubyte1_e32 v141, v162
	v_cvt_f32_ubyte2_e32 v142, v162
	v_cvt_f32_ubyte3_e32 v143, v162
	v_pk_mul_f32 v[144:145], v[144:145], s[16:17] op_sel_hi:[1,0]
	v_pk_mul_f32 v[146:147], v[146:147], s[16:17] op_sel_hi:[1,0]
	v_pk_mul_f32 v[140:141], v[140:141], s[16:17] op_sel_hi:[1,0]
	v_pk_mul_f32 v[142:143], v[142:143], s[16:17] op_sel_hi:[1,0]
	v_max_f32_e32 v144, 0xda24260, v144
	v_max_f32_e32 v145, 0xda24260, v145
	v_max_f32_e32 v146, 0xda24260, v146
	v_max_f32_e32 v147, 0xda24260, v147
	v_rcp_f32_e32 v144, v144
	v_rcp_f32_e32 v145, v145
	v_rcp_f32_e32 v146, v146
	v_rcp_f32_e32 v147, v147
	v_pk_mul_f32 v[140:141], v[140:141], v[144:145]
	v_pk_mul_f32 v[142:143], v[142:143], v[146:147]
	v_pk_mul_f32 v[48:49], v[48:49], v[140:141]
	v_pk_mul_f32 v[50:51], v[50:51], v[142:143]
	v_cvt_f32_ubyte0_e32 v144, v167
	v_cvt_f32_ubyte1_e32 v145, v167
	v_cvt_f32_ubyte2_e32 v146, v167
	v_cvt_f32_ubyte3_e32 v147, v167
	v_cvt_f32_ubyte0_e32 v140, v163
	v_cvt_f32_ubyte1_e32 v141, v163
	v_cvt_f32_ubyte2_e32 v142, v163
	v_cvt_f32_ubyte3_e32 v143, v163
	v_pk_mul_f32 v[144:145], v[144:145], s[16:17] op_sel_hi:[1,0]
	v_pk_mul_f32 v[146:147], v[146:147], s[16:17] op_sel_hi:[1,0]
	v_pk_mul_f32 v[140:141], v[140:141], s[16:17] op_sel_hi:[1,0]
	v_pk_mul_f32 v[142:143], v[142:143], s[16:17] op_sel_hi:[1,0]
	v_max_f32_e32 v144, 0xda24260, v144
	v_max_f32_e32 v145, 0xda24260, v145
	v_max_f32_e32 v146, 0xda24260, v146
	v_max_f32_e32 v147, 0xda24260, v147
	v_rcp_f32_e32 v144, v144
	v_rcp_f32_e32 v145, v145
	v_rcp_f32_e32 v146, v146
	v_rcp_f32_e32 v147, v147
	v_pk_mul_f32 v[140:141], v[140:141], v[144:145]
	v_pk_mul_f32 v[142:143], v[142:143], v[146:147]
	v_pk_mul_f32 v[40:41], v[40:41], v[140:141]
	v_pk_mul_f32 v[42:43], v[42:43], v[142:143]
	s_waitcnt vmcnt(10)
	v_permlane16_swap_b32 v168, v169
	v_permlane16_swap_b32 v170, v171
	v_permlane16_swap_b32 v172, v173
	v_permlane16_swap_b32 v174, v175
	v_permlane32_swap_b32 v168, v170
	v_permlane32_swap_b32 v169, v171
	v_permlane32_swap_b32 v172, v174
	v_permlane32_swap_b32 v173, v175
	v_cvt_f32_ubyte0_e32 v144, v172
	v_cvt_f32_ubyte1_e32 v145, v172
	v_cvt_f32_ubyte2_e32 v146, v172
	v_cvt_f32_ubyte3_e32 v147, v172
	v_cvt_f32_ubyte0_e32 v140, v168
	v_cvt_f32_ubyte1_e32 v141, v168
	v_cvt_f32_ubyte2_e32 v142, v168
	v_cvt_f32_ubyte3_e32 v143, v168
	v_pk_mul_f32 v[144:145], v[144:145], s[16:17] op_sel_hi:[1,0]
	v_pk_mul_f32 v[146:147], v[146:147], s[16:17] op_sel_hi:[1,0]
	v_pk_mul_f32 v[140:141], v[140:141], s[16:17] op_sel_hi:[1,0]
	v_pk_mul_f32 v[142:143], v[142:143], s[16:17] op_sel_hi:[1,0]
	v_max_f32_e32 v144, 0xda24260, v144
	v_max_f32_e32 v145, 0xda24260, v145
	v_max_f32_e32 v146, 0xda24260, v146
	v_max_f32_e32 v147, 0xda24260, v147
	v_rcp_f32_e32 v144, v144
	v_rcp_f32_e32 v145, v145
	v_rcp_f32_e32 v146, v146
	v_rcp_f32_e32 v147, v147
	v_pk_mul_f32 v[140:141], v[140:141], v[144:145]
	v_pk_mul_f32 v[142:143], v[142:143], v[146:147]
	v_pk_mul_f32 v[124:125], v[124:125], v[140:141]
	v_pk_mul_f32 v[126:127], v[126:127], v[142:143]
	v_cvt_f32_ubyte0_e32 v144, v173
	v_cvt_f32_ubyte1_e32 v145, v173
	v_cvt_f32_ubyte2_e32 v146, v173
	v_cvt_f32_ubyte3_e32 v147, v173
	v_cvt_f32_ubyte0_e32 v140, v169
	v_cvt_f32_ubyte1_e32 v141, v169
	v_cvt_f32_ubyte2_e32 v142, v169
	v_cvt_f32_ubyte3_e32 v143, v169
; __device__ __forceinline__ float u8f(unsigned w, int i) { return (float)((w >> (8 * i)) & 0xffu) * (1.f / 255.f); }
; __device__ void phase4(const Params& p) {
;     ...
;             #pragma unroll
;             for (int ai = 0; ai < 2; ++ai)
;               #pragma unroll
;               for (int m = 0; m < 4; ++m) {
;                 const unsigned ga = pa[(ai * 128 + m * 16) / 4];
;                 const unsigned gb = pb[(ai * 128 + m * 16) / 4];
;                 #pragma unroll
;                 for (int j = 0; j < 4; ++j)
;                   acc[ai][bj][m][n][j] *= u8f(ga, j) * __builtin_amdgcn_rcpf(fmaxf(u8f(gb, j), 1e-30f));
	v_pk_mul_f32 v[144:145], v[144:145], s[16:17] op_sel_hi:[1,0]
	v_pk_mul_f32 v[146:147], v[146:147], s[16:17] op_sel_hi:[1,0]
	v_pk_mul_f32 v[140:141], v[140:141], s[16:17] op_sel_hi:[1,0]
	v_pk_mul_f32 v[142:143], v[142:143], s[16:17] op_sel_hi:[1,0]
	v_max_f32_e32 v144, 0xda24260, v144
	v_max_f32_e32 v145, 0xda24260, v145
	v_max_f32_e32 v146, 0xda24260, v146
	v_max_f32_e32 v147, 0xda24260, v147
	v_rcp_f32_e32 v144, v144
	v_rcp_f32_e32 v145, v145
	v_rcp_f32_e32 v146, v146
	v_rcp_f32_e32 v147, v147
	v_pk_mul_f32 v[140:141], v[140:141], v[144:145]
	v_pk_mul_f32 v[142:143], v[142:143], v[146:147]
	v_pk_mul_f32 v[116:117], v[116:117], v[140:141]
	v_pk_mul_f32 v[118:119], v[118:119], v[142:143]
	v_cvt_f32_ubyte0_e32 v144, v174
	v_cvt_f32_ubyte1_e32 v145, v174
	v_cvt_f32_ubyte2_e32 v146, v174
	v_cvt_f32_ubyte3_e32 v147, v174
	v_cvt_f32_ubyte0_e32 v140, v170
	v_cvt_f32_ubyte1_e32 v141, v170
	v_cvt_f32_ubyte2_e32 v142, v170
	v_cvt_f32_ubyte3_e32 v143, v170
	v_pk_mul_f32 v[144:145], v[144:145], s[16:17] op_sel_hi:[1,0]
	v_pk_mul_f32 v[146:147], v[146:147], s[16:17] op_sel_hi:[1,0]
	v_pk_mul_f32 v[140:141], v[140:141], s[16:17] op_sel_hi:[1,0]
	v_pk_mul_f32 v[142:143], v[142:143], s[16:17] op_sel_hi:[1,0]
	v_max_f32_e32 v144, 0xda24260, v144
	v_max_f32_e32 v145, 0xda24260, v145
	v_max_f32_e32 v146, 0xda24260, v146
	v_max_f32_e32 v147, 0xda24260, v147
	v_rcp_f32_e32 v144, v144
	v_rcp_f32_e32 v145, v145
	v_rcp_f32_e32 v146, v146
	v_rcp_f32_e32 v147, v147
	v_pk_mul_f32 v[140:141], v[140:141], v[144:145]
	v_pk_mul_f32 v[142:143], v[142:143], v[146:147]
	v_pk_mul_f32 v[108:109], v[108:109], v[140:141]
	v_pk_mul_f32 v[110:111], v[110:111], v[142:143]
	v_cvt_f32_ubyte0_e32 v144, v175
	v_cvt_f32_ubyte1_e32 v145, v175
	v_cvt_f32_ubyte2_e32 v146, v175
	v_cvt_f32_ubyte3_e32 v147, v175
	v_cvt_f32_ubyte0_e32 v140, v171
	v_cvt_f32_ubyte1_e32 v141, v171
	v_cvt_f32_ubyte2_e32 v142, v171
	v_cvt_f32_ubyte3_e32 v143, v171
	v_pk_mul_f32 v[144:145], v[144:145], s[16:17] op_sel_hi:[1,0]
	v_pk_mul_f32 v[146:147], v[146:147], s[16:17] op_sel_hi:[1,0]
	v_pk_mul_f32 v[140:141], v[140:141], s[16:17] op_sel_hi:[1,0]
	v_pk_mul_f32 v[142:143], v[142:143], s[16:17] op_sel_hi:[1,0]
	v_max_f32_e32 v144, 0xda24260, v144
	v_max_f32_e32 v145, 0xda24260, v145
	v_max_f32_e32 v146, 0xda24260, v146
	v_max_f32_e32 v147, 0xda24260, v147
	v_rcp_f32_e32 v144, v144
	v_rcp_f32_e32 v145, v145
	v_rcp_f32_e32 v146, v146
	v_rcp_f32_e32 v147, v147
	v_pk_mul_f32 v[140:141], v[140:141], v[144:145]
	v_pk_mul_f32 v[142:143], v[142:143], v[146:147]
	v_pk_mul_f32 v[100:101], v[100:101], v[140:141]
	v_pk_mul_f32 v[102:103], v[102:103], v[142:143]
	s_waitcnt vmcnt(8)
	v_permlane16_swap_b32 v176, v177
	v_permlane16_swap_b32 v178, v179
	v_permlane16_swap_b32 v180, v181
	v_permlane16_swap_b32 v182, v183
	v_permlane32_swap_b32 v176, v178
	v_permlane32_swap_b32 v177, v179
	v_permlane32_swap_b32 v180, v182
	v_permlane32_swap_b32 v181, v183
	v_cvt_f32_ubyte0_e32 v144, v180
	v_cvt_f32_ubyte1_e32 v145, v180
	v_cvt_f32_ubyte2_e32 v146, v180
	v_cvt_f32_ubyte3_e32 v147, v180
	v_cvt_f32_ubyte0_e32 v140, v176
	v_cvt_f32_ubyte1_e32 v141, v176
	v_cvt_f32_ubyte2_e32 v142, v176
	v_cvt_f32_ubyte3_e32 v143, v176
	v_pk_mul_f32 v[144:145], v[144:145], s[16:17] op_sel_hi:[1,0]
	v_pk_mul_f32 v[146:147], v[146:147], s[16:17] op_sel_hi:[1,0]
	v_pk_mul_f32 v[140:141], v[140:141], s[16:17] op_sel_hi:[1,0]
	v_pk_mul_f32 v[142:143], v[142:143], s[16:17] op_sel_hi:[1,0]
	v_max_f32_e32 v144, 0xda24260, v144
	v_max_f32_e32 v145, 0xda24260, v145
	v_max_f32_e32 v146, 0xda24260, v146
	v_max_f32_e32 v147, 0xda24260, v147
	v_rcp_f32_e32 v144, v144
	v_rcp_f32_e32 v145, v145
	v_rcp_f32_e32 v146, v146
	v_rcp_f32_e32 v147, v147
	v_pk_mul_f32 v[140:141], v[140:141], v[144:145]
	v_pk_mul_f32 v[142:143], v[142:143], v[146:147]
	v_pk_mul_f32 v[60:61], v[60:61], v[140:141]
	v_pk_mul_f32 v[62:63], v[62:63], v[142:143]
	v_cvt_f32_ubyte0_e32 v144, v181
	v_cvt_f32_ubyte1_e32 v145, v181
	v_cvt_f32_ubyte2_e32 v146, v181
	v_cvt_f32_ubyte3_e32 v147, v181
	v_cvt_f32_ubyte0_e32 v140, v177
	v_cvt_f32_ubyte1_e32 v141, v177
	v_cvt_f32_ubyte2_e32 v142, v177
	v_cvt_f32_ubyte3_e32 v143, v177
	v_pk_mul_f32 v[144:145], v[144:145], s[16:17] op_sel_hi:[1,0]
	v_pk_mul_f32 v[146:147], v[146:147], s[16:17] op_sel_hi:[1,0]
	v_pk_mul_f32 v[140:141], v[140:141], s[16:17] op_sel_hi:[1,0]
	v_pk_mul_f32 v[142:143], v[142:143], s[16:17] op_sel_hi:[1,0]
	v_max_f32_e32 v144, 0xda24260, v144
	v_max_f32_e32 v145, 0xda24260, v145
	v_max_f32_e32 v146, 0xda24260, v146
	v_max_f32_e32 v147, 0xda24260, v147
	v_rcp_f32_e32 v144, v144
	v_rcp_f32_e32 v145, v145
	v_rcp_f32_e32 v146, v146
	v_rcp_f32_e32 v147, v147
	v_pk_mul_f32 v[140:141], v[140:141], v[144:145]
	v_pk_mul_f32 v[142:143], v[142:143], v[146:147]
	v_pk_mul_f32 v[52:53], v[52:53], v[140:141]
	v_pk_mul_f32 v[54:55], v[54:55], v[142:143]
	v_cvt_f32_ubyte0_e32 v144, v182
	v_cvt_f32_ubyte1_e32 v145, v182
	v_cvt_f32_ubyte2_e32 v146, v182
	v_cvt_f32_ubyte3_e32 v147, v182
	v_cvt_f32_ubyte0_e32 v140, v178
	v_cvt_f32_ubyte1_e32 v141, v178
	v_cvt_f32_ubyte2_e32 v142, v178
	v_cvt_f32_ubyte3_e32 v143, v178
	v_pk_mul_f32 v[144:145], v[144:145], s[16:17] op_sel_hi:[1,0]
	v_pk_mul_f32 v[146:147], v[146:147], s[16:17] op_sel_hi:[1,0]
	v_pk_mul_f32 v[140:141], v[140:141], s[16:17] op_sel_hi:[1,0]
	v_pk_mul_f32 v[142:143], v[142:143], s[16:17] op_sel_hi:[1,0]
	v_max_f32_e32 v144, 0xda24260, v144
	v_max_f32_e32 v145, 0xda24260, v145
	v_max_f32_e32 v146, 0xda24260, v146
	v_max_f32_e32 v147, 0xda24260, v147
	v_rcp_f32_e32 v144, v144
	v_rcp_f32_e32 v145, v145
	v_rcp_f32_e32 v146, v146
	v_rcp_f32_e32 v147, v147
	v_pk_mul_f32 v[140:141], v[140:141], v[144:145]
	v_pk_mul_f32 v[142:143], v[142:143], v[146:147]
	v_pk_mul_f32 v[44:45], v[44:45], v[140:141]
	v_pk_mul_f32 v[46:47], v[46:47], v[142:143]
	v_cvt_f32_ubyte0_e32 v144, v183
	v_cvt_f32_ubyte1_e32 v145, v183
	v_cvt_f32_ubyte2_e32 v146, v183
	v_cvt_f32_ubyte3_e32 v147, v183
	v_cvt_f32_ubyte0_e32 v140, v179
	v_cvt_f32_ubyte1_e32 v141, v179
	v_cvt_f32_ubyte2_e32 v142, v179
	v_cvt_f32_ubyte3_e32 v143, v179
	v_pk_mul_f32 v[144:145], v[144:145], s[16:17] op_sel_hi:[1,0]
	v_pk_mul_f32 v[146:147], v[146:147], s[16:17] op_sel_hi:[1,0]
	v_pk_mul_f32 v[140:141], v[140:141], s[16:17] op_sel_hi:[1,0]
	v_pk_mul_f32 v[142:143], v[142:143], s[16:17] op_sel_hi:[1,0]
	v_max_f32_e32 v144, 0xda24260, v144
	v_max_f32_e32 v145, 0xda24260, v145
	v_max_f32_e32 v146, 0xda24260, v146
	v_max_f32_e32 v147, 0xda24260, v147
	v_rcp_f32_e32 v144, v144
	v_rcp_f32_e32 v145, v145
	v_rcp_f32_e32 v146, v146
	v_rcp_f32_e32 v147, v147
	v_pk_mul_f32 v[140:141], v[140:141], v[144:145]
	v_pk_mul_f32 v[142:143], v[142:143], v[146:147]
	v_pk_mul_f32 v[36:37], v[36:37], v[140:141]
	v_pk_mul_f32 v[38:39], v[38:39], v[142:143]
	s_waitcnt vmcnt(6)
; __device__ __forceinline__ float u8f(unsigned w, int i) { return (float)((w >> (8 * i)) & 0xffu) * (1.f / 255.f); }
; __device__ void phase4(const Params& p) {
;     ...
;             #pragma unroll
;             for (int ai = 0; ai < 2; ++ai)
;               #pragma unroll
;               for (int m = 0; m < 4; ++m) {
;                 const unsigned ga = pa[(ai * 128 + m * 16) / 4];
;                 const unsigned gb = pb[(ai * 128 + m * 16) / 4];
;                 #pragma unroll
;                 for (int j = 0; j < 4; ++j)
;                   acc[ai][bj][m][n][j] *= u8f(ga, j) * __builtin_amdgcn_rcpf(fmaxf(u8f(gb, j), 1e-30f));
	v_permlane16_swap_b32 v184, v185
	v_permlane16_swap_b32 v186, v187
	v_permlane16_swap_b32 v188, v189
	v_permlane16_swap_b32 v190, v191
	v_permlane32_swap_b32 v184, v186
	v_permlane32_swap_b32 v185, v187
	v_permlane32_swap_b32 v188, v190
	v_permlane32_swap_b32 v189, v191
	v_cvt_f32_ubyte0_e32 v144, v188
	v_cvt_f32_ubyte1_e32 v145, v188
	v_cvt_f32_ubyte2_e32 v146, v188
	v_cvt_f32_ubyte3_e32 v147, v188
	v_cvt_f32_ubyte0_e32 v140, v184
	v_cvt_f32_ubyte1_e32 v141, v184
	v_cvt_f32_ubyte2_e32 v142, v184
	v_cvt_f32_ubyte3_e32 v143, v184
	v_pk_mul_f32 v[144:145], v[144:145], s[16:17] op_sel_hi:[1,0]
	v_pk_mul_f32 v[146:147], v[146:147], s[16:17] op_sel_hi:[1,0]
	v_pk_mul_f32 v[140:141], v[140:141], s[16:17] op_sel_hi:[1,0]
	v_pk_mul_f32 v[142:143], v[142:143], s[16:17] op_sel_hi:[1,0]
	v_max_f32_e32 v144, 0xda24260, v144
	v_max_f32_e32 v145, 0xda24260, v145
	v_max_f32_e32 v146, 0xda24260, v146
	v_max_f32_e32 v147, 0xda24260, v147
	v_rcp_f32_e32 v144, v144
	v_rcp_f32_e32 v145, v145
	v_rcp_f32_e32 v146, v146
	v_rcp_f32_e32 v147, v147
	v_pk_mul_f32 v[140:141], v[140:141], v[144:145]
	v_pk_mul_f32 v[142:143], v[142:143], v[146:147]
	v_pk_mul_f32 v[96:97], v[96:97], v[140:141]
	v_pk_mul_f32 v[98:99], v[98:99], v[142:143]
	v_cvt_f32_ubyte0_e32 v144, v189
	v_cvt_f32_ubyte1_e32 v145, v189
	v_cvt_f32_ubyte2_e32 v146, v189
	v_cvt_f32_ubyte3_e32 v147, v189
	v_cvt_f32_ubyte0_e32 v140, v185
	v_cvt_f32_ubyte1_e32 v141, v185
	v_cvt_f32_ubyte2_e32 v142, v185
	v_cvt_f32_ubyte3_e32 v143, v185
	v_pk_mul_f32 v[144:145], v[144:145], s[16:17] op_sel_hi:[1,0]
	v_pk_mul_f32 v[146:147], v[146:147], s[16:17] op_sel_hi:[1,0]
	v_pk_mul_f32 v[140:141], v[140:141], s[16:17] op_sel_hi:[1,0]
	v_pk_mul_f32 v[142:143], v[142:143], s[16:17] op_sel_hi:[1,0]
	v_max_f32_e32 v144, 0xda24260, v144
	v_max_f32_e32 v145, 0xda24260, v145
	v_max_f32_e32 v146, 0xda24260, v146
	v_max_f32_e32 v147, 0xda24260, v147
	v_rcp_f32_e32 v144, v144
	v_rcp_f32_e32 v145, v145
	v_rcp_f32_e32 v146, v146
	v_rcp_f32_e32 v147, v147
	v_pk_mul_f32 v[140:141], v[140:141], v[144:145]
	v_pk_mul_f32 v[142:143], v[142:143], v[146:147]
	v_pk_mul_f32 v[88:89], v[88:89], v[140:141]
	v_pk_mul_f32 v[90:91], v[90:91], v[142:143]
	v_cvt_f32_ubyte0_e32 v144, v190
	v_cvt_f32_ubyte1_e32 v145, v190
	v_cvt_f32_ubyte2_e32 v146, v190
	v_cvt_f32_ubyte3_e32 v147, v190
	v_cvt_f32_ubyte0_e32 v140, v186
	v_cvt_f32_ubyte1_e32 v141, v186
	v_cvt_f32_ubyte2_e32 v142, v186
	v_cvt_f32_ubyte3_e32 v143, v186
	v_pk_mul_f32 v[144:145], v[144:145], s[16:17] op_sel_hi:[1,0]
	v_pk_mul_f32 v[146:147], v[146:147], s[16:17] op_sel_hi:[1,0]
	v_pk_mul_f32 v[140:141], v[140:141], s[16:17] op_sel_hi:[1,0]
	v_pk_mul_f32 v[142:143], v[142:143], s[16:17] op_sel_hi:[1,0]
	v_max_f32_e32 v144, 0xda24260, v144
	v_max_f32_e32 v145, 0xda24260, v145
	v_max_f32_e32 v146, 0xda24260, v146
	v_max_f32_e32 v147, 0xda24260, v147
	v_rcp_f32_e32 v144, v144
	v_rcp_f32_e32 v145, v145
	v_rcp_f32_e32 v146, v146
	v_rcp_f32_e32 v147, v147
	v_pk_mul_f32 v[140:141], v[140:141], v[144:145]
	v_pk_mul_f32 v[142:143], v[142:143], v[146:147]
	v_pk_mul_f32 v[80:81], v[80:81], v[140:141]
	v_pk_mul_f32 v[82:83], v[82:83], v[142:143]
	v_cvt_f32_ubyte0_e32 v144, v191
	v_cvt_f32_ubyte1_e32 v145, v191
	v_cvt_f32_ubyte2_e32 v146, v191
	v_cvt_f32_ubyte3_e32 v147, v191
	v_cvt_f32_ubyte0_e32 v140, v187
	v_cvt_f32_ubyte1_e32 v141, v187
	v_cvt_f32_ubyte2_e32 v142, v187
	v_cvt_f32_ubyte3_e32 v143, v187
	v_pk_mul_f32 v[144:145], v[144:145], s[16:17] op_sel_hi:[1,0]
	v_pk_mul_f32 v[146:147], v[146:147], s[16:17] op_sel_hi:[1,0]
	v_pk_mul_f32 v[140:141], v[140:141], s[16:17] op_sel_hi:[1,0]
	v_pk_mul_f32 v[142:143], v[142:143], s[16:17] op_sel_hi:[1,0]
	v_max_f32_e32 v144, 0xda24260, v144
	v_max_f32_e32 v145, 0xda24260, v145
	v_max_f32_e32 v146, 0xda24260, v146
	v_max_f32_e32 v147, 0xda24260, v147
	v_rcp_f32_e32 v144, v144
	v_rcp_f32_e32 v145, v145
	v_rcp_f32_e32 v146, v146
	v_rcp_f32_e32 v147, v147
	v_pk_mul_f32 v[140:141], v[140:141], v[144:145]
	v_pk_mul_f32 v[142:143], v[142:143], v[146:147]
	v_pk_mul_f32 v[72:73], v[72:73], v[140:141]
	v_pk_mul_f32 v[74:75], v[74:75], v[142:143]
	s_waitcnt vmcnt(4)
	v_permlane16_swap_b32 v196, v197
	v_permlane16_swap_b32 v198, v199
	v_permlane16_swap_b32 v200, v201
	v_permlane16_swap_b32 v202, v203
	v_permlane32_swap_b32 v196, v198
	v_permlane32_swap_b32 v197, v199
	v_permlane32_swap_b32 v200, v202
	v_permlane32_swap_b32 v201, v203
	v_cvt_f32_ubyte0_e32 v144, v200
	v_cvt_f32_ubyte1_e32 v145, v200
	v_cvt_f32_ubyte2_e32 v146, v200
	v_cvt_f32_ubyte3_e32 v147, v200
	v_cvt_f32_ubyte0_e32 v140, v196
	v_cvt_f32_ubyte1_e32 v141, v196
	v_cvt_f32_ubyte2_e32 v142, v196
	v_cvt_f32_ubyte3_e32 v143, v196
	v_pk_mul_f32 v[144:145], v[144:145], s[16:17] op_sel_hi:[1,0]
	v_pk_mul_f32 v[146:147], v[146:147], s[16:17] op_sel_hi:[1,0]
	v_pk_mul_f32 v[140:141], v[140:141], s[16:17] op_sel_hi:[1,0]
	v_pk_mul_f32 v[142:143], v[142:143], s[16:17] op_sel_hi:[1,0]
	v_max_f32_e32 v144, 0xda24260, v144
	v_max_f32_e32 v145, 0xda24260, v145
	v_max_f32_e32 v146, 0xda24260, v146
	v_max_f32_e32 v147, 0xda24260, v147
	v_rcp_f32_e32 v144, v144
	v_rcp_f32_e32 v145, v145
	v_rcp_f32_e32 v146, v146
	v_rcp_f32_e32 v147, v147
	v_pk_mul_f32 v[140:141], v[140:141], v[144:145]
	v_pk_mul_f32 v[142:143], v[142:143], v[146:147]
	v_pk_mul_f32 v[32:33], v[32:33], v[140:141]
	v_pk_mul_f32 v[34:35], v[34:35], v[142:143]
	v_cvt_f32_ubyte0_e32 v144, v201
	v_cvt_f32_ubyte1_e32 v145, v201
	v_cvt_f32_ubyte2_e32 v146, v201
	v_cvt_f32_ubyte3_e32 v147, v201
	v_cvt_f32_ubyte0_e32 v140, v197
	v_cvt_f32_ubyte1_e32 v141, v197
	v_cvt_f32_ubyte2_e32 v142, v197
	v_cvt_f32_ubyte3_e32 v143, v197
	v_pk_mul_f32 v[144:145], v[144:145], s[16:17] op_sel_hi:[1,0]
; __device__ __forceinline__ float u8f(unsigned w, int i) { return (float)((w >> (8 * i)) & 0xffu) * (1.f / 255.f); }
; __device__ void phase4(const Params& p) {
;     ...
;             #pragma unroll
;             for (int ai = 0; ai < 2; ++ai)
;               #pragma unroll
;               for (int m = 0; m < 4; ++m) {
;                 const unsigned ga = pa[(ai * 128 + m * 16) / 4];
;                 const unsigned gb = pb[(ai * 128 + m * 16) / 4];
;                 #pragma unroll
;                 for (int j = 0; j < 4; ++j)
;                   acc[ai][bj][m][n][j] *= u8f(ga, j) * __builtin_amdgcn_rcpf(fmaxf(u8f(gb, j), 1e-30f));
	v_pk_mul_f32 v[146:147], v[146:147], s[16:17] op_sel_hi:[1,0]
	v_pk_mul_f32 v[140:141], v[140:141], s[16:17] op_sel_hi:[1,0]
	v_pk_mul_f32 v[142:143], v[142:143], s[16:17] op_sel_hi:[1,0]
	v_max_f32_e32 v144, 0xda24260, v144
	v_max_f32_e32 v145, 0xda24260, v145
	v_max_f32_e32 v146, 0xda24260, v146
	v_max_f32_e32 v147, 0xda24260, v147
	v_rcp_f32_e32 v144, v144
	v_rcp_f32_e32 v145, v145
	v_rcp_f32_e32 v146, v146
	v_rcp_f32_e32 v147, v147
	v_pk_mul_f32 v[140:141], v[140:141], v[144:145]
	v_pk_mul_f32 v[142:143], v[142:143], v[146:147]
	v_pk_mul_f32 v[24:25], v[24:25], v[140:141]
	v_pk_mul_f32 v[26:27], v[26:27], v[142:143]
	v_cvt_f32_ubyte0_e32 v144, v202
	v_cvt_f32_ubyte1_e32 v145, v202
	v_cvt_f32_ubyte2_e32 v146, v202
	v_cvt_f32_ubyte3_e32 v147, v202
	v_cvt_f32_ubyte0_e32 v140, v198
	v_cvt_f32_ubyte1_e32 v141, v198
	v_cvt_f32_ubyte2_e32 v142, v198
	v_cvt_f32_ubyte3_e32 v143, v198
	v_pk_mul_f32 v[144:145], v[144:145], s[16:17] op_sel_hi:[1,0]
	v_pk_mul_f32 v[146:147], v[146:147], s[16:17] op_sel_hi:[1,0]
	v_pk_mul_f32 v[140:141], v[140:141], s[16:17] op_sel_hi:[1,0]
	v_pk_mul_f32 v[142:143], v[142:143], s[16:17] op_sel_hi:[1,0]
	v_max_f32_e32 v144, 0xda24260, v144
	v_max_f32_e32 v145, 0xda24260, v145
	v_max_f32_e32 v146, 0xda24260, v146
	v_max_f32_e32 v147, 0xda24260, v147
	v_rcp_f32_e32 v144, v144
	v_rcp_f32_e32 v145, v145
	v_rcp_f32_e32 v146, v146
	v_rcp_f32_e32 v147, v147
	v_pk_mul_f32 v[140:141], v[140:141], v[144:145]
	v_pk_mul_f32 v[142:143], v[142:143], v[146:147]
	v_pk_mul_f32 v[16:17], v[16:17], v[140:141]
	v_pk_mul_f32 v[18:19], v[18:19], v[142:143]
	v_cvt_f32_ubyte0_e32 v144, v203
	v_cvt_f32_ubyte1_e32 v145, v203
	v_cvt_f32_ubyte2_e32 v146, v203
	v_cvt_f32_ubyte3_e32 v147, v203
	v_cvt_f32_ubyte0_e32 v140, v199
	v_cvt_f32_ubyte1_e32 v141, v199
	v_cvt_f32_ubyte2_e32 v142, v199
	v_cvt_f32_ubyte3_e32 v143, v199
	v_pk_mul_f32 v[144:145], v[144:145], s[16:17] op_sel_hi:[1,0]
	v_pk_mul_f32 v[146:147], v[146:147], s[16:17] op_sel_hi:[1,0]
	v_pk_mul_f32 v[140:141], v[140:141], s[16:17] op_sel_hi:[1,0]
	v_pk_mul_f32 v[142:143], v[142:143], s[16:17] op_sel_hi:[1,0]
	v_max_f32_e32 v144, 0xda24260, v144
	v_max_f32_e32 v145, 0xda24260, v145
	v_max_f32_e32 v146, 0xda24260, v146
	v_max_f32_e32 v147, 0xda24260, v147
	v_rcp_f32_e32 v144, v144
	v_rcp_f32_e32 v145, v145
	v_rcp_f32_e32 v146, v146
	v_rcp_f32_e32 v147, v147
	v_pk_mul_f32 v[140:141], v[140:141], v[144:145]
	v_pk_mul_f32 v[142:143], v[142:143], v[146:147]
	v_pk_mul_f32 v[8:9], v[8:9], v[140:141]
	v_pk_mul_f32 v[10:11], v[10:11], v[142:143]
	s_waitcnt vmcnt(2)
	v_permlane16_swap_b32 v204, v205
	v_permlane16_swap_b32 v206, v207
	v_permlane16_swap_b32 v208, v209
	v_permlane16_swap_b32 v210, v211
	v_permlane32_swap_b32 v204, v206
	v_permlane32_swap_b32 v205, v207
	v_permlane32_swap_b32 v208, v210
	v_permlane32_swap_b32 v209, v211
	v_cvt_f32_ubyte0_e32 v144, v208
	v_cvt_f32_ubyte1_e32 v145, v208
	v_cvt_f32_ubyte2_e32 v146, v208
	v_cvt_f32_ubyte3_e32 v147, v208
	v_cvt_f32_ubyte0_e32 v140, v204
	v_cvt_f32_ubyte1_e32 v141, v204
	v_cvt_f32_ubyte2_e32 v142, v204
	v_cvt_f32_ubyte3_e32 v143, v204
	v_pk_mul_f32 v[144:145], v[144:145], s[16:17] op_sel_hi:[1,0]
	v_pk_mul_f32 v[146:147], v[146:147], s[16:17] op_sel_hi:[1,0]
	v_pk_mul_f32 v[140:141], v[140:141], s[16:17] op_sel_hi:[1,0]
	v_pk_mul_f32 v[142:143], v[142:143], s[16:17] op_sel_hi:[1,0]
	v_max_f32_e32 v144, 0xda24260, v144
	v_max_f32_e32 v145, 0xda24260, v145
	v_max_f32_e32 v146, 0xda24260, v146
	v_max_f32_e32 v147, 0xda24260, v147
	v_rcp_f32_e32 v144, v144
	v_rcp_f32_e32 v145, v145
	v_rcp_f32_e32 v146, v146
	v_rcp_f32_e32 v147, v147
	v_pk_mul_f32 v[140:141], v[140:141], v[144:145]
	v_pk_mul_f32 v[142:143], v[142:143], v[146:147]
	v_pk_mul_f32 v[92:93], v[92:93], v[140:141]
	v_pk_mul_f32 v[94:95], v[94:95], v[142:143]
	v_cvt_f32_ubyte0_e32 v144, v209
	v_cvt_f32_ubyte1_e32 v145, v209
	v_cvt_f32_ubyte2_e32 v146, v209
	v_cvt_f32_ubyte3_e32 v147, v209
	v_cvt_f32_ubyte0_e32 v140, v205
	v_cvt_f32_ubyte1_e32 v141, v205
	v_cvt_f32_ubyte2_e32 v142, v205
	v_cvt_f32_ubyte3_e32 v143, v205
	v_pk_mul_f32 v[144:145], v[144:145], s[16:17] op_sel_hi:[1,0]
	v_pk_mul_f32 v[146:147], v[146:147], s[16:17] op_sel_hi:[1,0]
	v_pk_mul_f32 v[140:141], v[140:141], s[16:17] op_sel_hi:[1,0]
	v_pk_mul_f32 v[142:143], v[142:143], s[16:17] op_sel_hi:[1,0]
	v_max_f32_e32 v144, 0xda24260, v144
	v_max_f32_e32 v145, 0xda24260, v145
	v_max_f32_e32 v146, 0xda24260, v146
	v_max_f32_e32 v147, 0xda24260, v147
	v_rcp_f32_e32 v144, v144
	v_rcp_f32_e32 v145, v145
	v_rcp_f32_e32 v146, v146
	v_rcp_f32_e32 v147, v147
	v_pk_mul_f32 v[140:141], v[140:141], v[144:145]
	v_pk_mul_f32 v[142:143], v[142:143], v[146:147]
	v_pk_mul_f32 v[84:85], v[84:85], v[140:141]
	v_pk_mul_f32 v[86:87], v[86:87], v[142:143]
	v_cvt_f32_ubyte0_e32 v144, v210
	v_cvt_f32_ubyte1_e32 v145, v210
	v_cvt_f32_ubyte2_e32 v146, v210
	v_cvt_f32_ubyte3_e32 v147, v210
	v_cvt_f32_ubyte0_e32 v140, v206
	v_cvt_f32_ubyte1_e32 v141, v206
	v_cvt_f32_ubyte2_e32 v142, v206
	v_cvt_f32_ubyte3_e32 v143, v206
	v_pk_mul_f32 v[144:145], v[144:145], s[16:17] op_sel_hi:[1,0]
	v_pk_mul_f32 v[146:147], v[146:147], s[16:17] op_sel_hi:[1,0]
	v_pk_mul_f32 v[140:141], v[140:141], s[16:17] op_sel_hi:[1,0]
	v_pk_mul_f32 v[142:143], v[142:143], s[16:17] op_sel_hi:[1,0]
	v_max_f32_e32 v144, 0xda24260, v144
	v_max_f32_e32 v145, 0xda24260, v145
	v_max_f32_e32 v146, 0xda24260, v146
	v_max_f32_e32 v147, 0xda24260, v147
	v_rcp_f32_e32 v144, v144
	v_rcp_f32_e32 v145, v145
	v_rcp_f32_e32 v146, v146
	v_rcp_f32_e32 v147, v147
	v_pk_mul_f32 v[140:141], v[140:141], v[144:145]
	v_pk_mul_f32 v[142:143], v[142:143], v[146:147]
	v_pk_mul_f32 v[76:77], v[76:77], v[140:141]
	v_pk_mul_f32 v[78:79], v[78:79], v[142:143]
	v_cvt_f32_ubyte0_e32 v144, v211
	v_cvt_f32_ubyte1_e32 v145, v211
	v_cvt_f32_ubyte2_e32 v146, v211
	v_cvt_f32_ubyte3_e32 v147, v211
	v_cvt_f32_ubyte0_e32 v140, v207
	v_cvt_f32_ubyte1_e32 v141, v207
	v_cvt_f32_ubyte2_e32 v142, v207
	v_cvt_f32_ubyte3_e32 v143, v207
	v_pk_mul_f32 v[144:145], v[144:145], s[16:17] op_sel_hi:[1,0]
	v_pk_mul_f32 v[146:147], v[146:147], s[16:17] op_sel_hi:[1,0]
	v_pk_mul_f32 v[140:141], v[140:141], s[16:17] op_sel_hi:[1,0]
	v_pk_mul_f32 v[142:143], v[142:143], s[16:17] op_sel_hi:[1,0]
	v_max_f32_e32 v144, 0xda24260, v144
	v_max_f32_e32 v145, 0xda24260, v145
	v_max_f32_e32 v146, 0xda24260, v146
	v_max_f32_e32 v147, 0xda24260, v147
	v_rcp_f32_e32 v144, v144
	v_rcp_f32_e32 v145, v145
	v_rcp_f32_e32 v146, v146
	v_rcp_f32_e32 v147, v147
	v_pk_mul_f32 v[140:141], v[140:141], v[144:145]
	v_pk_mul_f32 v[142:143], v[142:143], v[146:147]
	v_pk_mul_f32 v[68:69], v[68:69], v[140:141]
	v_pk_mul_f32 v[70:71], v[70:71], v[142:143]
	s_waitcnt vmcnt(0)
; __device__ __forceinline__ float u8f(unsigned w, int i) { return (float)((w >> (8 * i)) & 0xffu) * (1.f / 255.f); }
; __device__ void phase4(const Params& p) {
;     ...
;             #pragma unroll
;             for (int ai = 0; ai < 2; ++ai)
;               #pragma unroll
;               for (int m = 0; m < 4; ++m) {
;                 const unsigned ga = pa[(ai * 128 + m * 16) / 4];
;                 const unsigned gb = pb[(ai * 128 + m * 16) / 4];
;                 #pragma unroll
;                 for (int j = 0; j < 4; ++j)
;                   acc[ai][bj][m][n][j] *= u8f(ga, j) * __builtin_amdgcn_rcpf(fmaxf(u8f(gb, j), 1e-30f));
;     ...
;       } else {
;         #pragma unroll
;         for (int bj = 0; bj < 2; ++bj) {
;           unsigned gB[2][2][4];
;           #pragma unroll
;           for (int n = 0; n < 2; ++n) {
;             const size_t base = (size_t)EPI_T(bj, n) * D + lanef;
;             const unsigned* pb = reinterpret_cast<const unsigned*>(reinterpret_cast<const unsigned char*>(sgb) + base);
;             #pragma unroll
;             for (int ai = 0; ai < 2; ++ai)
;               #pragma unroll
;               for (int m = 0; m < 4; ++m) gB[n][ai][m] = pb[(ai * 128 + m * 16) / 4];
;           }
;           #pragma unroll
;           for (int n = 0; n < 2; ++n) {
;             const size_t base = (size_t)EPI_T(bj, n) * D + lanef;
;             v2u* po = reinterpret_cast<v2u*>(mo + base);
;             #pragma unroll
;             for (int ai = 0; ai < 2; ++ai)
;               #pragma unroll
;               for (int m = 0; m < 4; ++m) {
;                 const unsigned gb = gB[n][ai][m];
;                 v2u o;
;                 o.x = pk2(acc[ai][bj][m][n][0] * fmaxf(u8f(gb, 0), 1e-30f), acc[ai][bj][m][n][1] * fmaxf(u8f(gb, 1), 1e-30f));
;                 o.y = pk2(acc[ai][bj][m][n][2] * fmaxf(u8f(gb, 2), 1e-30f), acc[ai][bj][m][n][3] * fmaxf(u8f(gb, 3), 1e-30f));
;                 po[(ai * 128 + m * 16) / 4] = o;
	v_permlane16_swap_b32 v212, v213
	v_permlane16_swap_b32 v214, v215
	v_permlane16_swap_b32 v216, v217
	v_permlane16_swap_b32 v218, v219
	v_permlane32_swap_b32 v212, v214
	v_permlane32_swap_b32 v213, v215
	v_permlane32_swap_b32 v216, v218
	v_permlane32_swap_b32 v217, v219
	v_cvt_f32_ubyte0_e32 v144, v216
	v_cvt_f32_ubyte1_e32 v145, v216
	v_cvt_f32_ubyte2_e32 v146, v216
	v_cvt_f32_ubyte3_e32 v147, v216
	v_cvt_f32_ubyte0_e32 v140, v212
	v_cvt_f32_ubyte1_e32 v141, v212
	v_cvt_f32_ubyte2_e32 v142, v212
	v_cvt_f32_ubyte3_e32 v143, v212
	v_pk_mul_f32 v[144:145], v[144:145], s[16:17] op_sel_hi:[1,0]
	v_pk_mul_f32 v[146:147], v[146:147], s[16:17] op_sel_hi:[1,0]
	v_pk_mul_f32 v[140:141], v[140:141], s[16:17] op_sel_hi:[1,0]
	v_pk_mul_f32 v[142:143], v[142:143], s[16:17] op_sel_hi:[1,0]
	v_max_f32_e32 v144, 0xda24260, v144
	v_max_f32_e32 v145, 0xda24260, v145
	v_max_f32_e32 v146, 0xda24260, v146
	v_max_f32_e32 v147, 0xda24260, v147
	v_rcp_f32_e32 v144, v144
	v_rcp_f32_e32 v145, v145
	v_rcp_f32_e32 v146, v146
	v_rcp_f32_e32 v147, v147
	v_pk_mul_f32 v[140:141], v[140:141], v[144:145]
	v_pk_mul_f32 v[142:143], v[142:143], v[146:147]
	v_pk_mul_f32 v[28:29], v[28:29], v[140:141]
	v_pk_mul_f32 v[30:31], v[30:31], v[142:143]
	v_cvt_f32_ubyte0_e32 v144, v217
	v_cvt_f32_ubyte1_e32 v145, v217
	v_cvt_f32_ubyte2_e32 v146, v217
	v_cvt_f32_ubyte3_e32 v147, v217
	v_cvt_f32_ubyte0_e32 v140, v213
	v_cvt_f32_ubyte1_e32 v141, v213
	v_cvt_f32_ubyte2_e32 v142, v213
	v_cvt_f32_ubyte3_e32 v143, v213
	v_pk_mul_f32 v[144:145], v[144:145], s[16:17] op_sel_hi:[1,0]
	v_pk_mul_f32 v[146:147], v[146:147], s[16:17] op_sel_hi:[1,0]
	v_pk_mul_f32 v[140:141], v[140:141], s[16:17] op_sel_hi:[1,0]
	v_pk_mul_f32 v[142:143], v[142:143], s[16:17] op_sel_hi:[1,0]
	v_max_f32_e32 v144, 0xda24260, v144
	v_max_f32_e32 v145, 0xda24260, v145
	v_max_f32_e32 v146, 0xda24260, v146
	v_max_f32_e32 v147, 0xda24260, v147
	v_rcp_f32_e32 v144, v144
	v_rcp_f32_e32 v145, v145
	v_rcp_f32_e32 v146, v146
	v_rcp_f32_e32 v147, v147
	v_pk_mul_f32 v[140:141], v[140:141], v[144:145]
	v_pk_mul_f32 v[142:143], v[142:143], v[146:147]
	v_pk_mul_f32 v[20:21], v[20:21], v[140:141]
	v_pk_mul_f32 v[22:23], v[22:23], v[142:143]
	v_cvt_f32_ubyte0_e32 v144, v218
	v_cvt_f32_ubyte1_e32 v145, v218
	v_cvt_f32_ubyte2_e32 v146, v218
	v_cvt_f32_ubyte3_e32 v147, v218
	v_cvt_f32_ubyte0_e32 v140, v214
	v_cvt_f32_ubyte1_e32 v141, v214
	v_cvt_f32_ubyte2_e32 v142, v214
	v_cvt_f32_ubyte3_e32 v143, v214
	v_pk_mul_f32 v[144:145], v[144:145], s[16:17] op_sel_hi:[1,0]
	v_pk_mul_f32 v[146:147], v[146:147], s[16:17] op_sel_hi:[1,0]
	v_pk_mul_f32 v[140:141], v[140:141], s[16:17] op_sel_hi:[1,0]
	v_pk_mul_f32 v[142:143], v[142:143], s[16:17] op_sel_hi:[1,0]
	v_max_f32_e32 v144, 0xda24260, v144
	v_max_f32_e32 v145, 0xda24260, v145
	v_max_f32_e32 v146, 0xda24260, v146
	v_max_f32_e32 v147, 0xda24260, v147
	v_rcp_f32_e32 v144, v144
	v_rcp_f32_e32 v145, v145
	v_rcp_f32_e32 v146, v146
	v_rcp_f32_e32 v147, v147
	v_pk_mul_f32 v[140:141], v[140:141], v[144:145]
	v_pk_mul_f32 v[142:143], v[142:143], v[146:147]
	v_pk_mul_f32 v[12:13], v[12:13], v[140:141]
	v_pk_mul_f32 v[14:15], v[14:15], v[142:143]
	v_cvt_f32_ubyte0_e32 v144, v219
	v_cvt_f32_ubyte1_e32 v145, v219
	v_cvt_f32_ubyte2_e32 v146, v219
	v_cvt_f32_ubyte3_e32 v147, v219
	v_cvt_f32_ubyte0_e32 v140, v215
	v_cvt_f32_ubyte1_e32 v141, v215
	v_cvt_f32_ubyte2_e32 v142, v215
	v_cvt_f32_ubyte3_e32 v143, v215
	v_pk_mul_f32 v[144:145], v[144:145], s[16:17] op_sel_hi:[1,0]
	v_pk_mul_f32 v[146:147], v[146:147], s[16:17] op_sel_hi:[1,0]
	v_pk_mul_f32 v[140:141], v[140:141], s[16:17] op_sel_hi:[1,0]
	v_pk_mul_f32 v[142:143], v[142:143], s[16:17] op_sel_hi:[1,0]
	v_max_f32_e32 v144, 0xda24260, v144
	v_max_f32_e32 v145, 0xda24260, v145
	v_max_f32_e32 v146, 0xda24260, v146
	v_max_f32_e32 v147, 0xda24260, v147
	v_rcp_f32_e32 v144, v144
	v_rcp_f32_e32 v145, v145
	v_rcp_f32_e32 v146, v146
	v_rcp_f32_e32 v147, v147
	v_pk_mul_f32 v[140:141], v[140:141], v[144:145]
	v_pk_mul_f32 v[142:143], v[142:143], v[146:147]
	v_pk_mul_f32 v[4:5], v[4:5], v[140:141]
	v_pk_mul_f32 v[6:7], v[6:7], v[142:143]
	s_branch .LBB0_599
.Lp4e_seg1:
	global_load_dwordx4 v[152:155], v136, s[12:13]
	global_load_dwordx4 v[156:159], v136, s[12:13] offset:128
	global_load_dwordx4 v[160:163], v137, s[12:13]
	global_load_dwordx4 v[164:167], v137, s[12:13] offset:128
	global_load_dwordx4 v[168:171], v138, s[12:13]
	global_load_dwordx4 v[172:175], v138, s[12:13] offset:128
	global_load_dwordx4 v[176:179], v139, s[12:13]
	global_load_dwordx4 v[180:183], v139, s[12:13] offset:128
	v_and_b32_e32 v140, 1, v134
	v_lshlrev_b32_e32 v141, 2, v134
	v_mad_u32_u24 v141, v140, 12, v141
	v_add3_u32 v141, v141, v135, s20
	v_lshl_add_u32 v141, v132, 11, v141
	v_lshlrev_b32_e32 v220, 1, v141
	v_add_u32_e32 v221, 0x10000, v220
	v_add_u32_e32 v222, 0x80000, v220
	v_add_u32_e32 v223, 0x90000, v220
	s_waitcnt vmcnt(7)
; __device__ __forceinline__ float u8f(unsigned w, int i) { return (float)((w >> (8 * i)) & 0xffu) * (1.f / 255.f); }
; __device__ void phase4(const Params& p) {
;     ...
;           for (int n = 0; n < 2; ++n) {
;             const size_t base = (size_t)EPI_T(bj, n) * D + lanef;
;             const unsigned* pb = reinterpret_cast<const unsigned*>(reinterpret_cast<const unsigned char*>(sgb) + base);
;             #pragma unroll
;             for (int ai = 0; ai < 2; ++ai)
;               #pragma unroll
;               for (int m = 0; m < 4; ++m) gB[n][ai][m] = pb[(ai * 128 + m * 16) / 4];
;           }
;           #pragma unroll
;           for (int n = 0; n < 2; ++n) {
;             const size_t base = (size_t)EPI_T(bj, n) * D + lanef;
;             v2u* po = reinterpret_cast<v2u*>(mo + base);
;             #pragma unroll
;             for (int ai = 0; ai < 2; ++ai)
;               #pragma unroll
;               for (int m = 0; m < 4; ++m) {
;                 const unsigned gb = gB[n][ai][m];
;                 v2u o;
;                 o.x = pk2(acc[ai][bj][m][n][0] * fmaxf(u8f(gb, 0), 1e-30f), acc[ai][bj][m][n][1] * fmaxf(u8f(gb, 1), 1e-30f));
;                 o.y = pk2(acc[ai][bj][m][n][2] * fmaxf(u8f(gb, 2), 1e-30f), acc[ai][bj][m][n][3] * fmaxf(u8f(gb, 3), 1e-30f));
;                 po[(ai * 128 + m * 16) / 4] = o;
	v_permlane16_swap_b32 v152, v153
	v_permlane16_swap_b32 v154, v155
	s_nop 1
	v_permlane32_swap_b32 v152, v154
	v_permlane32_swap_b32 v153, v155
	v_cvt_f32_ubyte0_e32 v144, v152
	v_cvt_f32_ubyte1_e32 v145, v152
	v_cvt_f32_ubyte2_e32 v146, v152
	v_cvt_f32_ubyte3_e32 v147, v152
	v_pk_mul_f32 v[144:145], v[144:145], s[16:17] op_sel_hi:[1,0]
	v_pk_mul_f32 v[146:147], v[146:147], s[16:17] op_sel_hi:[1,0]
	v_max_f32_e32 v144, 0xda24260, v144
	v_max_f32_e32 v145, 0xda24260, v145
	v_max_f32_e32 v146, 0xda24260, v146
	v_max_f32_e32 v147, 0xda24260, v147
	v_pk_mul_f32 v[128:129], v[128:129], v[144:145]
	v_pk_mul_f32 v[130:131], v[130:131], v[146:147]
	v_cvt_f32_ubyte0_e32 v144, v153
	v_cvt_f32_ubyte1_e32 v145, v153
	v_cvt_f32_ubyte2_e32 v146, v153
	v_cvt_f32_ubyte3_e32 v147, v153
	v_pk_mul_f32 v[144:145], v[144:145], s[16:17] op_sel_hi:[1,0]
	v_pk_mul_f32 v[146:147], v[146:147], s[16:17] op_sel_hi:[1,0]
	v_max_f32_e32 v144, 0xda24260, v144
	v_max_f32_e32 v145, 0xda24260, v145
	v_max_f32_e32 v146, 0xda24260, v146
	v_max_f32_e32 v147, 0xda24260, v147
	v_pk_mul_f32 v[120:121], v[120:121], v[144:145]
	v_pk_mul_f32 v[122:123], v[122:123], v[146:147]
	v_cvt_f32_ubyte0_e32 v144, v154
	v_cvt_f32_ubyte1_e32 v145, v154
	v_cvt_f32_ubyte2_e32 v146, v154
	v_cvt_f32_ubyte3_e32 v147, v154
	v_pk_mul_f32 v[144:145], v[144:145], s[16:17] op_sel_hi:[1,0]
	v_pk_mul_f32 v[146:147], v[146:147], s[16:17] op_sel_hi:[1,0]
	v_max_f32_e32 v144, 0xda24260, v144
	v_max_f32_e32 v145, 0xda24260, v145
	v_max_f32_e32 v146, 0xda24260, v146
	v_max_f32_e32 v147, 0xda24260, v147
	v_pk_mul_f32 v[112:113], v[112:113], v[144:145]
	v_pk_mul_f32 v[114:115], v[114:115], v[146:147]
	v_cvt_f32_ubyte0_e32 v144, v155
	v_cvt_f32_ubyte1_e32 v145, v155
	v_cvt_f32_ubyte2_e32 v146, v155
	v_cvt_f32_ubyte3_e32 v147, v155
	v_pk_mul_f32 v[144:145], v[144:145], s[16:17] op_sel_hi:[1,0]
	v_pk_mul_f32 v[146:147], v[146:147], s[16:17] op_sel_hi:[1,0]
	v_max_f32_e32 v144, 0xda24260, v144
	v_max_f32_e32 v145, 0xda24260, v145
	v_max_f32_e32 v146, 0xda24260, v146
	v_max_f32_e32 v147, 0xda24260, v147
	v_pk_mul_f32 v[104:105], v[104:105], v[144:145]
	v_pk_mul_f32 v[106:107], v[106:107], v[146:147]
	v_cvt_pk_bf16_f32 v128, v128, v129
	v_cvt_pk_bf16_f32 v129, v130, v131
	v_cvt_pk_bf16_f32 v130, v120, v121
	v_cvt_pk_bf16_f32 v131, v122, v123
	v_cvt_pk_bf16_f32 v112, v112, v113
	v_cvt_pk_bf16_f32 v113, v114, v115
	v_cvt_pk_bf16_f32 v114, v104, v105
	v_cvt_pk_bf16_f32 v115, v106, v107
	s_nop 1
	v_permlane16_swap_b32 v128, v130
	v_permlane16_swap_b32 v129, v131
	v_permlane16_swap_b32 v112, v114
	v_permlane16_swap_b32 v113, v115
	global_store_dwordx4 v220, v[128:131], s[42:43]
	global_store_dwordx4 v220, v[112:115], s[42:43] offset:64
	s_waitcnt vmcnt(8)
	v_permlane16_swap_b32 v156, v157
	v_permlane16_swap_b32 v158, v159
	s_nop 1
	v_permlane32_swap_b32 v156, v158
	v_permlane32_swap_b32 v157, v159
	v_cvt_f32_ubyte0_e32 v144, v156
	v_cvt_f32_ubyte1_e32 v145, v156
	v_cvt_f32_ubyte2_e32 v146, v156
	v_cvt_f32_ubyte3_e32 v147, v156
	v_pk_mul_f32 v[144:145], v[144:145], s[16:17] op_sel_hi:[1,0]
	v_pk_mul_f32 v[146:147], v[146:147], s[16:17] op_sel_hi:[1,0]
	v_max_f32_e32 v144, 0xda24260, v144
	v_max_f32_e32 v145, 0xda24260, v145
	v_max_f32_e32 v146, 0xda24260, v146
	v_max_f32_e32 v147, 0xda24260, v147
	v_pk_mul_f32 v[64:65], v[64:65], v[144:145]
	v_pk_mul_f32 v[66:67], v[66:67], v[146:147]
	v_cvt_f32_ubyte0_e32 v144, v157
	v_cvt_f32_ubyte1_e32 v145, v157
	v_cvt_f32_ubyte2_e32 v146, v157
	v_cvt_f32_ubyte3_e32 v147, v157
	v_pk_mul_f32 v[144:145], v[144:145], s[16:17] op_sel_hi:[1,0]
	v_pk_mul_f32 v[146:147], v[146:147], s[16:17] op_sel_hi:[1,0]
	v_max_f32_e32 v144, 0xda24260, v144
	v_max_f32_e32 v145, 0xda24260, v145
	v_max_f32_e32 v146, 0xda24260, v146
	v_max_f32_e32 v147, 0xda24260, v147
	v_pk_mul_f32 v[56:57], v[56:57], v[144:145]
	v_pk_mul_f32 v[58:59], v[58:59], v[146:147]
	v_cvt_f32_ubyte0_e32 v144, v158
	v_cvt_f32_ubyte1_e32 v145, v158
	v_cvt_f32_ubyte2_e32 v146, v158
	v_cvt_f32_ubyte3_e32 v147, v158
	v_pk_mul_f32 v[144:145], v[144:145], s[16:17] op_sel_hi:[1,0]
	v_pk_mul_f32 v[146:147], v[146:147], s[16:17] op_sel_hi:[1,0]
	v_max_f32_e32 v144, 0xda24260, v144
	v_max_f32_e32 v145, 0xda24260, v145
	v_max_f32_e32 v146, 0xda24260, v146
	v_max_f32_e32 v147, 0xda24260, v147
	v_pk_mul_f32 v[48:49], v[48:49], v[144:145]
	v_pk_mul_f32 v[50:51], v[50:51], v[146:147]
	v_cvt_f32_ubyte0_e32 v144, v159
	v_cvt_f32_ubyte1_e32 v145, v159
	v_cvt_f32_ubyte2_e32 v146, v159
	v_cvt_f32_ubyte3_e32 v147, v159
	v_pk_mul_f32 v[144:145], v[144:145], s[16:17] op_sel_hi:[1,0]
	v_pk_mul_f32 v[146:147], v[146:147], s[16:17] op_sel_hi:[1,0]
	v_max_f32_e32 v144, 0xda24260, v144
	v_max_f32_e32 v145, 0xda24260, v145
	v_max_f32_e32 v146, 0xda24260, v146
	v_max_f32_e32 v147, 0xda24260, v147
	v_pk_mul_f32 v[40:41], v[40:41], v[144:145]
	v_pk_mul_f32 v[42:43], v[42:43], v[146:147]
	v_cvt_pk_bf16_f32 v64, v64, v65
	v_cvt_pk_bf16_f32 v65, v66, v67
	v_cvt_pk_bf16_f32 v66, v56, v57
	v_cvt_pk_bf16_f32 v67, v58, v59
	v_cvt_pk_bf16_f32 v48, v48, v49
	v_cvt_pk_bf16_f32 v49, v50, v51
	v_cvt_pk_bf16_f32 v50, v40, v41
	v_cvt_pk_bf16_f32 v51, v42, v43
	s_nop 1
	v_permlane16_swap_b32 v64, v66
	v_permlane16_swap_b32 v65, v67
	v_permlane16_swap_b32 v48, v50
	v_permlane16_swap_b32 v49, v51
	global_store_dwordx4 v220, v[64:67], s[42:43] offset:256
	global_store_dwordx4 v220, v[48:51], s[42:43] offset:320
	s_waitcnt vmcnt(9)
; __device__ __forceinline__ float u8f(unsigned w, int i) { return (float)((w >> (8 * i)) & 0xffu) * (1.f / 255.f); }
; __device__ void phase4(const Params& p) {
;     ...
;         #pragma unroll
;         for (int bj = 0; bj < 2; ++bj) {
;           unsigned gB[2][2][4];
;           #pragma unroll
;           for (int n = 0; n < 2; ++n) {
;             const size_t base = (size_t)EPI_T(bj, n) * D + lanef;
;             const unsigned* pb = reinterpret_cast<const unsigned*>(reinterpret_cast<const unsigned char*>(sgb) + base);
;             #pragma unroll
;             for (int ai = 0; ai < 2; ++ai)
;               #pragma unroll
;               for (int m = 0; m < 4; ++m) gB[n][ai][m] = pb[(ai * 128 + m * 16) / 4];
;           }
;           #pragma unroll
;           for (int n = 0; n < 2; ++n) {
;             const size_t base = (size_t)EPI_T(bj, n) * D + lanef;
;             v2u* po = reinterpret_cast<v2u*>(mo + base);
;             #pragma unroll
;             for (int ai = 0; ai < 2; ++ai)
;               #pragma unroll
;               for (int m = 0; m < 4; ++m) {
;                 const unsigned gb = gB[n][ai][m];
;                 v2u o;
;                 o.x = pk2(acc[ai][bj][m][n][0] * fmaxf(u8f(gb, 0), 1e-30f), acc[ai][bj][m][n][1] * fmaxf(u8f(gb, 1), 1e-30f));
;                 o.y = pk2(acc[ai][bj][m][n][2] * fmaxf(u8f(gb, 2), 1e-30f), acc[ai][bj][m][n][3] * fmaxf(u8f(gb, 3), 1e-30f));
;                 po[(ai * 128 + m * 16) / 4] = o;
;               }
;           }
;           asm volatile("" ::: "memory");
;         }
	v_permlane16_swap_b32 v160, v161
	v_permlane16_swap_b32 v162, v163
	s_nop 1
	v_permlane32_swap_b32 v160, v162
	v_permlane32_swap_b32 v161, v163
	v_cvt_f32_ubyte0_e32 v144, v160
	v_cvt_f32_ubyte1_e32 v145, v160
	v_cvt_f32_ubyte2_e32 v146, v160
	v_cvt_f32_ubyte3_e32 v147, v160
	v_pk_mul_f32 v[144:145], v[144:145], s[16:17] op_sel_hi:[1,0]
	v_pk_mul_f32 v[146:147], v[146:147], s[16:17] op_sel_hi:[1,0]
	v_max_f32_e32 v144, 0xda24260, v144
	v_max_f32_e32 v145, 0xda24260, v145
	v_max_f32_e32 v146, 0xda24260, v146
	v_max_f32_e32 v147, 0xda24260, v147
	v_pk_mul_f32 v[124:125], v[124:125], v[144:145]
	v_pk_mul_f32 v[126:127], v[126:127], v[146:147]
	v_cvt_f32_ubyte0_e32 v144, v161
	v_cvt_f32_ubyte1_e32 v145, v161
	v_cvt_f32_ubyte2_e32 v146, v161
	v_cvt_f32_ubyte3_e32 v147, v161
	v_pk_mul_f32 v[144:145], v[144:145], s[16:17] op_sel_hi:[1,0]
	v_pk_mul_f32 v[146:147], v[146:147], s[16:17] op_sel_hi:[1,0]
	v_max_f32_e32 v144, 0xda24260, v144
	v_max_f32_e32 v145, 0xda24260, v145
	v_max_f32_e32 v146, 0xda24260, v146
	v_max_f32_e32 v147, 0xda24260, v147
	v_pk_mul_f32 v[116:117], v[116:117], v[144:145]
	v_pk_mul_f32 v[118:119], v[118:119], v[146:147]
	v_cvt_f32_ubyte0_e32 v144, v162
	v_cvt_f32_ubyte1_e32 v145, v162
	v_cvt_f32_ubyte2_e32 v146, v162
	v_cvt_f32_ubyte3_e32 v147, v162
	v_pk_mul_f32 v[144:145], v[144:145], s[16:17] op_sel_hi:[1,0]
	v_pk_mul_f32 v[146:147], v[146:147], s[16:17] op_sel_hi:[1,0]
	v_max_f32_e32 v144, 0xda24260, v144
	v_max_f32_e32 v145, 0xda24260, v145
	v_max_f32_e32 v146, 0xda24260, v146
	v_max_f32_e32 v147, 0xda24260, v147
	v_pk_mul_f32 v[108:109], v[108:109], v[144:145]
	v_pk_mul_f32 v[110:111], v[110:111], v[146:147]
	v_cvt_f32_ubyte0_e32 v144, v163
	v_cvt_f32_ubyte1_e32 v145, v163
	v_cvt_f32_ubyte2_e32 v146, v163
	v_cvt_f32_ubyte3_e32 v147, v163
	v_pk_mul_f32 v[144:145], v[144:145], s[16:17] op_sel_hi:[1,0]
	v_pk_mul_f32 v[146:147], v[146:147], s[16:17] op_sel_hi:[1,0]
	v_max_f32_e32 v144, 0xda24260, v144
	v_max_f32_e32 v145, 0xda24260, v145
	v_max_f32_e32 v146, 0xda24260, v146
	v_max_f32_e32 v147, 0xda24260, v147
	v_pk_mul_f32 v[100:101], v[100:101], v[144:145]
	v_pk_mul_f32 v[102:103], v[102:103], v[146:147]
	v_cvt_pk_bf16_f32 v124, v124, v125
	v_cvt_pk_bf16_f32 v125, v126, v127
	v_cvt_pk_bf16_f32 v126, v116, v117
	v_cvt_pk_bf16_f32 v127, v118, v119
	v_cvt_pk_bf16_f32 v108, v108, v109
	v_cvt_pk_bf16_f32 v109, v110, v111
	v_cvt_pk_bf16_f32 v110, v100, v101
	v_cvt_pk_bf16_f32 v111, v102, v103
	s_nop 1
	v_permlane16_swap_b32 v124, v126
	v_permlane16_swap_b32 v125, v127
	v_permlane16_swap_b32 v108, v110
	v_permlane16_swap_b32 v109, v111
	global_store_dwordx4 v221, v[124:127], s[42:43]
	global_store_dwordx4 v221, v[108:111], s[42:43] offset:64
	s_waitcnt vmcnt(10)
	v_permlane16_swap_b32 v164, v165
	v_permlane16_swap_b32 v166, v167
	s_nop 1
	v_permlane32_swap_b32 v164, v166
	v_permlane32_swap_b32 v165, v167
	v_cvt_f32_ubyte0_e32 v144, v164
	v_cvt_f32_ubyte1_e32 v145, v164
	v_cvt_f32_ubyte2_e32 v146, v164
	v_cvt_f32_ubyte3_e32 v147, v164
	v_pk_mul_f32 v[144:145], v[144:145], s[16:17] op_sel_hi:[1,0]
	v_pk_mul_f32 v[146:147], v[146:147], s[16:17] op_sel_hi:[1,0]
	v_max_f32_e32 v144, 0xda24260, v144
	v_max_f32_e32 v145, 0xda24260, v145
	v_max_f32_e32 v146, 0xda24260, v146
	v_max_f32_e32 v147, 0xda24260, v147
	v_pk_mul_f32 v[60:61], v[60:61], v[144:145]
	v_pk_mul_f32 v[62:63], v[62:63], v[146:147]
	v_cvt_f32_ubyte0_e32 v144, v165
	v_cvt_f32_ubyte1_e32 v145, v165
	v_cvt_f32_ubyte2_e32 v146, v165
	v_cvt_f32_ubyte3_e32 v147, v165
	v_pk_mul_f32 v[144:145], v[144:145], s[16:17] op_sel_hi:[1,0]
	v_pk_mul_f32 v[146:147], v[146:147], s[16:17] op_sel_hi:[1,0]
	v_max_f32_e32 v144, 0xda24260, v144
	v_max_f32_e32 v145, 0xda24260, v145
	v_max_f32_e32 v146, 0xda24260, v146
	v_max_f32_e32 v147, 0xda24260, v147
	v_pk_mul_f32 v[52:53], v[52:53], v[144:145]
	v_pk_mul_f32 v[54:55], v[54:55], v[146:147]
	v_cvt_f32_ubyte0_e32 v144, v166
	v_cvt_f32_ubyte1_e32 v145, v166
	v_cvt_f32_ubyte2_e32 v146, v166
	v_cvt_f32_ubyte3_e32 v147, v166
	v_pk_mul_f32 v[144:145], v[144:145], s[16:17] op_sel_hi:[1,0]
	v_pk_mul_f32 v[146:147], v[146:147], s[16:17] op_sel_hi:[1,0]
	v_max_f32_e32 v144, 0xda24260, v144
	v_max_f32_e32 v145, 0xda24260, v145
	v_max_f32_e32 v146, 0xda24260, v146
	v_max_f32_e32 v147, 0xda24260, v147
	v_pk_mul_f32 v[44:45], v[44:45], v[144:145]
	v_pk_mul_f32 v[46:47], v[46:47], v[146:147]
	v_cvt_f32_ubyte0_e32 v144, v167
	v_cvt_f32_ubyte1_e32 v145, v167
	v_cvt_f32_ubyte2_e32 v146, v167
	v_cvt_f32_ubyte3_e32 v147, v167
	v_pk_mul_f32 v[144:145], v[144:145], s[16:17] op_sel_hi:[1,0]
	v_pk_mul_f32 v[146:147], v[146:147], s[16:17] op_sel_hi:[1,0]
	v_max_f32_e32 v144, 0xda24260, v144
	v_max_f32_e32 v145, 0xda24260, v145
	v_max_f32_e32 v146, 0xda24260, v146
	v_max_f32_e32 v147, 0xda24260, v147
	v_pk_mul_f32 v[36:37], v[36:37], v[144:145]
	v_pk_mul_f32 v[38:39], v[38:39], v[146:147]
	v_cvt_pk_bf16_f32 v60, v60, v61
	v_cvt_pk_bf16_f32 v61, v62, v63
	v_cvt_pk_bf16_f32 v62, v52, v53
	v_cvt_pk_bf16_f32 v63, v54, v55
	v_cvt_pk_bf16_f32 v44, v44, v45
	v_cvt_pk_bf16_f32 v45, v46, v47
	v_cvt_pk_bf16_f32 v46, v36, v37
	v_cvt_pk_bf16_f32 v47, v38, v39
	s_nop 1
	v_permlane16_swap_b32 v60, v62
	v_permlane16_swap_b32 v61, v63
	v_permlane16_swap_b32 v44, v46
	v_permlane16_swap_b32 v45, v47
	global_store_dwordx4 v221, v[60:63], s[42:43] offset:256
	global_store_dwordx4 v221, v[44:47], s[42:43] offset:320
	s_waitcnt vmcnt(11)
; __device__ __forceinline__ float u8f(unsigned w, int i) { return (float)((w >> (8 * i)) & 0xffu) * (1.f / 255.f); }
; __device__ void phase4(const Params& p) {
;     ...
;         #pragma unroll
;         for (int bj = 0; bj < 2; ++bj) {
;           unsigned gB[2][2][4];
;           #pragma unroll
;           for (int n = 0; n < 2; ++n) {
;             const size_t base = (size_t)EPI_T(bj, n) * D + lanef;
;             const unsigned* pb = reinterpret_cast<const unsigned*>(reinterpret_cast<const unsigned char*>(sgb) + base);
;             #pragma unroll
;             for (int ai = 0; ai < 2; ++ai)
;               #pragma unroll
;               for (int m = 0; m < 4; ++m) gB[n][ai][m] = pb[(ai * 128 + m * 16) / 4];
;           }
;           #pragma unroll
;           for (int n = 0; n < 2; ++n) {
;             const size_t base = (size_t)EPI_T(bj, n) * D + lanef;
;             v2u* po = reinterpret_cast<v2u*>(mo + base);
;             #pragma unroll
;             for (int ai = 0; ai < 2; ++ai)
;               #pragma unroll
;               for (int m = 0; m < 4; ++m) {
;                 const unsigned gb = gB[n][ai][m];
;                 v2u o;
;                 o.x = pk2(acc[ai][bj][m][n][0] * fmaxf(u8f(gb, 0), 1e-30f), acc[ai][bj][m][n][1] * fmaxf(u8f(gb, 1), 1e-30f));
;                 o.y = pk2(acc[ai][bj][m][n][2] * fmaxf(u8f(gb, 2), 1e-30f), acc[ai][bj][m][n][3] * fmaxf(u8f(gb, 3), 1e-30f));
;                 po[(ai * 128 + m * 16) / 4] = o;
;               }
;           }
;           asm volatile("" ::: "memory");
;         }
	v_permlane16_swap_b32 v168, v169
	v_permlane16_swap_b32 v170, v171
	s_nop 1
	v_permlane32_swap_b32 v168, v170
	v_permlane32_swap_b32 v169, v171
	v_cvt_f32_ubyte0_e32 v144, v168
	v_cvt_f32_ubyte1_e32 v145, v168
	v_cvt_f32_ubyte2_e32 v146, v168
	v_cvt_f32_ubyte3_e32 v147, v168
	v_pk_mul_f32 v[144:145], v[144:145], s[16:17] op_sel_hi:[1,0]
	v_pk_mul_f32 v[146:147], v[146:147], s[16:17] op_sel_hi:[1,0]
	v_max_f32_e32 v144, 0xda24260, v144
	v_max_f32_e32 v145, 0xda24260, v145
	v_max_f32_e32 v146, 0xda24260, v146
	v_max_f32_e32 v147, 0xda24260, v147
	v_pk_mul_f32 v[96:97], v[96:97], v[144:145]
	v_pk_mul_f32 v[98:99], v[98:99], v[146:147]
	v_cvt_f32_ubyte0_e32 v144, v169
	v_cvt_f32_ubyte1_e32 v145, v169
	v_cvt_f32_ubyte2_e32 v146, v169
	v_cvt_f32_ubyte3_e32 v147, v169
	v_pk_mul_f32 v[144:145], v[144:145], s[16:17] op_sel_hi:[1,0]
	v_pk_mul_f32 v[146:147], v[146:147], s[16:17] op_sel_hi:[1,0]
	v_max_f32_e32 v144, 0xda24260, v144
	v_max_f32_e32 v145, 0xda24260, v145
	v_max_f32_e32 v146, 0xda24260, v146
	v_max_f32_e32 v147, 0xda24260, v147
	v_pk_mul_f32 v[88:89], v[88:89], v[144:145]
	v_pk_mul_f32 v[90:91], v[90:91], v[146:147]
	v_cvt_f32_ubyte0_e32 v144, v170
	v_cvt_f32_ubyte1_e32 v145, v170
	v_cvt_f32_ubyte2_e32 v146, v170
	v_cvt_f32_ubyte3_e32 v147, v170
	v_pk_mul_f32 v[144:145], v[144:145], s[16:17] op_sel_hi:[1,0]
	v_pk_mul_f32 v[146:147], v[146:147], s[16:17] op_sel_hi:[1,0]
	v_max_f32_e32 v144, 0xda24260, v144
	v_max_f32_e32 v145, 0xda24260, v145
	v_max_f32_e32 v146, 0xda24260, v146
	v_max_f32_e32 v147, 0xda24260, v147
	v_pk_mul_f32 v[80:81], v[80:81], v[144:145]
	v_pk_mul_f32 v[82:83], v[82:83], v[146:147]
	v_cvt_f32_ubyte0_e32 v144, v171
	v_cvt_f32_ubyte1_e32 v145, v171
	v_cvt_f32_ubyte2_e32 v146, v171
	v_cvt_f32_ubyte3_e32 v147, v171
	v_pk_mul_f32 v[144:145], v[144:145], s[16:17] op_sel_hi:[1,0]
	v_pk_mul_f32 v[146:147], v[146:147], s[16:17] op_sel_hi:[1,0]
	v_max_f32_e32 v144, 0xda24260, v144
	v_max_f32_e32 v145, 0xda24260, v145
	v_max_f32_e32 v146, 0xda24260, v146
	v_max_f32_e32 v147, 0xda24260, v147
	v_pk_mul_f32 v[72:73], v[72:73], v[144:145]
	v_pk_mul_f32 v[74:75], v[74:75], v[146:147]
	v_cvt_pk_bf16_f32 v96, v96, v97
	v_cvt_pk_bf16_f32 v97, v98, v99
	v_cvt_pk_bf16_f32 v98, v88, v89
	v_cvt_pk_bf16_f32 v99, v90, v91
	v_cvt_pk_bf16_f32 v80, v80, v81
	v_cvt_pk_bf16_f32 v81, v82, v83
	v_cvt_pk_bf16_f32 v82, v72, v73
	v_cvt_pk_bf16_f32 v83, v74, v75
	s_nop 1
	v_permlane16_swap_b32 v96, v98
	v_permlane16_swap_b32 v97, v99
	v_permlane16_swap_b32 v80, v82
	v_permlane16_swap_b32 v81, v83
	global_store_dwordx4 v222, v[96:99], s[42:43]
	global_store_dwordx4 v222, v[80:83], s[42:43] offset:64
	s_waitcnt vmcnt(12)
	v_permlane16_swap_b32 v172, v173
	v_permlane16_swap_b32 v174, v175
	s_nop 1
	v_permlane32_swap_b32 v172, v174
	v_permlane32_swap_b32 v173, v175
	v_cvt_f32_ubyte0_e32 v144, v172
	v_cvt_f32_ubyte1_e32 v145, v172
	v_cvt_f32_ubyte2_e32 v146, v172
	v_cvt_f32_ubyte3_e32 v147, v172
	v_pk_mul_f32 v[144:145], v[144:145], s[16:17] op_sel_hi:[1,0]
	v_pk_mul_f32 v[146:147], v[146:147], s[16:17] op_sel_hi:[1,0]
	v_max_f32_e32 v144, 0xda24260, v144
	v_max_f32_e32 v145, 0xda24260, v145
	v_max_f32_e32 v146, 0xda24260, v146
	v_max_f32_e32 v147, 0xda24260, v147
	v_pk_mul_f32 v[32:33], v[32:33], v[144:145]
	v_pk_mul_f32 v[34:35], v[34:35], v[146:147]
	v_cvt_f32_ubyte0_e32 v144, v173
	v_cvt_f32_ubyte1_e32 v145, v173
	v_cvt_f32_ubyte2_e32 v146, v173
	v_cvt_f32_ubyte3_e32 v147, v173
	v_pk_mul_f32 v[144:145], v[144:145], s[16:17] op_sel_hi:[1,0]
	v_pk_mul_f32 v[146:147], v[146:147], s[16:17] op_sel_hi:[1,0]
	v_max_f32_e32 v144, 0xda24260, v144
	v_max_f32_e32 v145, 0xda24260, v145
	v_max_f32_e32 v146, 0xda24260, v146
	v_max_f32_e32 v147, 0xda24260, v147
	v_pk_mul_f32 v[24:25], v[24:25], v[144:145]
	v_pk_mul_f32 v[26:27], v[26:27], v[146:147]
	v_cvt_f32_ubyte0_e32 v144, v174
	v_cvt_f32_ubyte1_e32 v145, v174
	v_cvt_f32_ubyte2_e32 v146, v174
	v_cvt_f32_ubyte3_e32 v147, v174
	v_pk_mul_f32 v[144:145], v[144:145], s[16:17] op_sel_hi:[1,0]
	v_pk_mul_f32 v[146:147], v[146:147], s[16:17] op_sel_hi:[1,0]
	v_max_f32_e32 v144, 0xda24260, v144
	v_max_f32_e32 v145, 0xda24260, v145
	v_max_f32_e32 v146, 0xda24260, v146
	v_max_f32_e32 v147, 0xda24260, v147
	v_pk_mul_f32 v[16:17], v[16:17], v[144:145]
	v_pk_mul_f32 v[18:19], v[18:19], v[146:147]
	v_cvt_f32_ubyte0_e32 v144, v175
	v_cvt_f32_ubyte1_e32 v145, v175
	v_cvt_f32_ubyte2_e32 v146, v175
	v_cvt_f32_ubyte3_e32 v147, v175
	v_pk_mul_f32 v[144:145], v[144:145], s[16:17] op_sel_hi:[1,0]
	v_pk_mul_f32 v[146:147], v[146:147], s[16:17] op_sel_hi:[1,0]
	v_max_f32_e32 v144, 0xda24260, v144
	v_max_f32_e32 v145, 0xda24260, v145
	v_max_f32_e32 v146, 0xda24260, v146
	v_max_f32_e32 v147, 0xda24260, v147
	v_pk_mul_f32 v[8:9], v[8:9], v[144:145]
	v_pk_mul_f32 v[10:11], v[10:11], v[146:147]
	v_cvt_pk_bf16_f32 v32, v32, v33
	v_cvt_pk_bf16_f32 v33, v34, v35
	v_cvt_pk_bf16_f32 v34, v24, v25
	v_cvt_pk_bf16_f32 v35, v26, v27
	v_cvt_pk_bf16_f32 v16, v16, v17
	v_cvt_pk_bf16_f32 v17, v18, v19
	v_cvt_pk_bf16_f32 v18, v8, v9
	v_cvt_pk_bf16_f32 v19, v10, v11
	s_nop 1
	v_permlane16_swap_b32 v32, v34
	v_permlane16_swap_b32 v33, v35
	v_permlane16_swap_b32 v16, v18
	v_permlane16_swap_b32 v17, v19
	global_store_dwordx4 v222, v[32:35], s[42:43] offset:256
	global_store_dwordx4 v222, v[16:19], s[42:43] offset:320
	s_waitcnt vmcnt(13)
; __device__ __forceinline__ float u8f(unsigned w, int i) { return (float)((w >> (8 * i)) & 0xffu) * (1.f / 255.f); }
; __device__ void phase4(const Params& p) {
;     ...
;         #pragma unroll
;         for (int bj = 0; bj < 2; ++bj) {
;           unsigned gB[2][2][4];
;           #pragma unroll
;           for (int n = 0; n < 2; ++n) {
;             const size_t base = (size_t)EPI_T(bj, n) * D + lanef;
;             const unsigned* pb = reinterpret_cast<const unsigned*>(reinterpret_cast<const unsigned char*>(sgb) + base);
;             #pragma unroll
;             for (int ai = 0; ai < 2; ++ai)
;               #pragma unroll
;               for (int m = 0; m < 4; ++m) gB[n][ai][m] = pb[(ai * 128 + m * 16) / 4];
;           }
;           #pragma unroll
;           for (int n = 0; n < 2; ++n) {
;             const size_t base = (size_t)EPI_T(bj, n) * D + lanef;
;             v2u* po = reinterpret_cast<v2u*>(mo + base);
;             #pragma unroll
;             for (int ai = 0; ai < 2; ++ai)
;               #pragma unroll
;               for (int m = 0; m < 4; ++m) {
;                 const unsigned gb = gB[n][ai][m];
;                 v2u o;
;                 o.x = pk2(acc[ai][bj][m][n][0] * fmaxf(u8f(gb, 0), 1e-30f), acc[ai][bj][m][n][1] * fmaxf(u8f(gb, 1), 1e-30f));
;                 o.y = pk2(acc[ai][bj][m][n][2] * fmaxf(u8f(gb, 2), 1e-30f), acc[ai][bj][m][n][3] * fmaxf(u8f(gb, 3), 1e-30f));
;                 po[(ai * 128 + m * 16) / 4] = o;
;               }
;           }
;           asm volatile("" ::: "memory");
;         }
	v_permlane16_swap_b32 v176, v177
	v_permlane16_swap_b32 v178, v179
	s_nop 1
	v_permlane32_swap_b32 v176, v178
	v_permlane32_swap_b32 v177, v179
	v_cvt_f32_ubyte0_e32 v144, v176
	v_cvt_f32_ubyte1_e32 v145, v176
	v_cvt_f32_ubyte2_e32 v146, v176
	v_cvt_f32_ubyte3_e32 v147, v176
	v_pk_mul_f32 v[144:145], v[144:145], s[16:17] op_sel_hi:[1,0]
	v_pk_mul_f32 v[146:147], v[146:147], s[16:17] op_sel_hi:[1,0]
	v_max_f32_e32 v144, 0xda24260, v144
	v_max_f32_e32 v145, 0xda24260, v145
	v_max_f32_e32 v146, 0xda24260, v146
	v_max_f32_e32 v147, 0xda24260, v147
	v_pk_mul_f32 v[92:93], v[92:93], v[144:145]
	v_pk_mul_f32 v[94:95], v[94:95], v[146:147]
	v_cvt_f32_ubyte0_e32 v144, v177
	v_cvt_f32_ubyte1_e32 v145, v177
	v_cvt_f32_ubyte2_e32 v146, v177
	v_cvt_f32_ubyte3_e32 v147, v177
	v_pk_mul_f32 v[144:145], v[144:145], s[16:17] op_sel_hi:[1,0]
	v_pk_mul_f32 v[146:147], v[146:147], s[16:17] op_sel_hi:[1,0]
	v_max_f32_e32 v144, 0xda24260, v144
	v_max_f32_e32 v145, 0xda24260, v145
	v_max_f32_e32 v146, 0xda24260, v146
	v_max_f32_e32 v147, 0xda24260, v147
	v_pk_mul_f32 v[84:85], v[84:85], v[144:145]
	v_pk_mul_f32 v[86:87], v[86:87], v[146:147]
	v_cvt_f32_ubyte0_e32 v144, v178
	v_cvt_f32_ubyte1_e32 v145, v178
	v_cvt_f32_ubyte2_e32 v146, v178
	v_cvt_f32_ubyte3_e32 v147, v178
	v_pk_mul_f32 v[144:145], v[144:145], s[16:17] op_sel_hi:[1,0]
	v_pk_mul_f32 v[146:147], v[146:147], s[16:17] op_sel_hi:[1,0]
	v_max_f32_e32 v144, 0xda24260, v144
	v_max_f32_e32 v145, 0xda24260, v145
	v_max_f32_e32 v146, 0xda24260, v146
	v_max_f32_e32 v147, 0xda24260, v147
	v_pk_mul_f32 v[76:77], v[76:77], v[144:145]
	v_pk_mul_f32 v[78:79], v[78:79], v[146:147]
	v_cvt_f32_ubyte0_e32 v144, v179
	v_cvt_f32_ubyte1_e32 v145, v179
	v_cvt_f32_ubyte2_e32 v146, v179
	v_cvt_f32_ubyte3_e32 v147, v179
	v_pk_mul_f32 v[144:145], v[144:145], s[16:17] op_sel_hi:[1,0]
	v_pk_mul_f32 v[146:147], v[146:147], s[16:17] op_sel_hi:[1,0]
	v_max_f32_e32 v144, 0xda24260, v144
	v_max_f32_e32 v145, 0xda24260, v145
	v_max_f32_e32 v146, 0xda24260, v146
	v_max_f32_e32 v147, 0xda24260, v147
	v_pk_mul_f32 v[68:69], v[68:69], v[144:145]
	v_pk_mul_f32 v[70:71], v[70:71], v[146:147]
	v_cvt_pk_bf16_f32 v92, v92, v93
	v_cvt_pk_bf16_f32 v93, v94, v95
	v_cvt_pk_bf16_f32 v94, v84, v85
	v_cvt_pk_bf16_f32 v95, v86, v87
	v_cvt_pk_bf16_f32 v76, v76, v77
	v_cvt_pk_bf16_f32 v77, v78, v79
	v_cvt_pk_bf16_f32 v78, v68, v69
	v_cvt_pk_bf16_f32 v79, v70, v71
	s_nop 1
	v_permlane16_swap_b32 v92, v94
	v_permlane16_swap_b32 v93, v95
	v_permlane16_swap_b32 v76, v78
	v_permlane16_swap_b32 v77, v79
	global_store_dwordx4 v223, v[92:95], s[42:43]
	global_store_dwordx4 v223, v[76:79], s[42:43] offset:64
	s_waitcnt vmcnt(14)
	v_permlane16_swap_b32 v180, v181
	v_permlane16_swap_b32 v182, v183
	s_nop 1
	v_permlane32_swap_b32 v180, v182
	v_permlane32_swap_b32 v181, v183
	v_cvt_f32_ubyte0_e32 v144, v180
	v_cvt_f32_ubyte1_e32 v145, v180
	v_cvt_f32_ubyte2_e32 v146, v180
	v_cvt_f32_ubyte3_e32 v147, v180
	v_pk_mul_f32 v[144:145], v[144:145], s[16:17] op_sel_hi:[1,0]
	v_pk_mul_f32 v[146:147], v[146:147], s[16:17] op_sel_hi:[1,0]
	v_max_f32_e32 v144, 0xda24260, v144
	v_max_f32_e32 v145, 0xda24260, v145
	v_max_f32_e32 v146, 0xda24260, v146
	v_max_f32_e32 v147, 0xda24260, v147
	v_pk_mul_f32 v[28:29], v[28:29], v[144:145]
	v_pk_mul_f32 v[30:31], v[30:31], v[146:147]
	v_cvt_f32_ubyte0_e32 v144, v181
	v_cvt_f32_ubyte1_e32 v145, v181
	v_cvt_f32_ubyte2_e32 v146, v181
	v_cvt_f32_ubyte3_e32 v147, v181
	v_pk_mul_f32 v[144:145], v[144:145], s[16:17] op_sel_hi:[1,0]
	v_pk_mul_f32 v[146:147], v[146:147], s[16:17] op_sel_hi:[1,0]
	v_max_f32_e32 v144, 0xda24260, v144
	v_max_f32_e32 v145, 0xda24260, v145
	v_max_f32_e32 v146, 0xda24260, v146
	v_max_f32_e32 v147, 0xda24260, v147
	v_pk_mul_f32 v[20:21], v[20:21], v[144:145]
	v_pk_mul_f32 v[22:23], v[22:23], v[146:147]
	v_cvt_f32_ubyte0_e32 v144, v182
	v_cvt_f32_ubyte1_e32 v145, v182
	v_cvt_f32_ubyte2_e32 v146, v182
	v_cvt_f32_ubyte3_e32 v147, v182
	v_pk_mul_f32 v[144:145], v[144:145], s[16:17] op_sel_hi:[1,0]
	v_pk_mul_f32 v[146:147], v[146:147], s[16:17] op_sel_hi:[1,0]
	v_max_f32_e32 v144, 0xda24260, v144
	v_max_f32_e32 v145, 0xda24260, v145
	v_max_f32_e32 v146, 0xda24260, v146
	v_max_f32_e32 v147, 0xda24260, v147
	v_pk_mul_f32 v[12:13], v[12:13], v[144:145]
	v_pk_mul_f32 v[14:15], v[14:15], v[146:147]
	v_cvt_f32_ubyte0_e32 v144, v183
	v_cvt_f32_ubyte1_e32 v145, v183
	v_cvt_f32_ubyte2_e32 v146, v183
	v_cvt_f32_ubyte3_e32 v147, v183
	v_pk_mul_f32 v[144:145], v[144:145], s[16:17] op_sel_hi:[1,0]
	v_pk_mul_f32 v[146:147], v[146:147], s[16:17] op_sel_hi:[1,0]
	v_max_f32_e32 v144, 0xda24260, v144
	v_max_f32_e32 v145, 0xda24260, v145
	v_max_f32_e32 v146, 0xda24260, v146
	v_max_f32_e32 v147, 0xda24260, v147
	v_pk_mul_f32 v[4:5], v[4:5], v[144:145]
	v_pk_mul_f32 v[6:7], v[6:7], v[146:147]
	v_cvt_pk_bf16_f32 v28, v28, v29
	v_cvt_pk_bf16_f32 v29, v30, v31
	v_cvt_pk_bf16_f32 v30, v20, v21
	v_cvt_pk_bf16_f32 v31, v22, v23
	v_cvt_pk_bf16_f32 v12, v12, v13
	v_cvt_pk_bf16_f32 v13, v14, v15
	v_cvt_pk_bf16_f32 v14, v4, v5
	v_cvt_pk_bf16_f32 v15, v6, v7
	s_nop 1
	v_permlane16_swap_b32 v28, v30
	v_permlane16_swap_b32 v29, v31
	v_permlane16_swap_b32 v12, v14
	v_permlane16_swap_b32 v13, v15
	global_store_dwordx4 v223, v[28:31], s[42:43] offset:256
	global_store_dwordx4 v223, v[12:15], s[42:43] offset:320
	s_branch .LBB0_599
